# XCD-local barriers between phases whose data stays on one XCD (p3b-p3c, p3c-hmat2-p4-p4b-p5, hmat-p1); hmat and p4b items remapped to the XCD that owns their rows
# speedup vs baseline: 1.0274x; 1.0179x over previous
.LBB0_135:
	s_cmp_gt_i32 s66, 1
	s_cselect_b64 s[2:3], -1, 0
	s_cmp_lt_i32 s67, 2
	s_cselect_b64 s[4:5], -1, 0
	s_or_b64 s[2:3], s[2:3], s[4:5]
	s_and_b64 vcc, exec, s[2:3]
	s_cbranch_vccnz .LBB0_189
	s_load_dwordx16 s[36:51], s[86:87], 0x0
	s_cmpk_gt_i32 s78, 0x3ff
	s_cbranch_scc1 .LBB0_139
	s_mov_b32 s100, s78
	s_mov_b32 s101, s64
	s_movk_i32 s99, 0x3ff
	s_cmpk_eq_i32 s64, 0x200
	s_cbranch_scc0 .Lhm_nomap_3
	s_and_b32 s99, s78, 7
	s_lshl_b32 s99, s99, 7
	s_lshr_b32 s100, s78, 3
	s_add_i32 s100, s100, s99
	s_add_i32 s99, s99, 0x7f
	s_movk_i32 s101, 64
.Lhm_nomap_3:
	s_add_u32 s4, s30, 0xc793e00
	s_addc_u32 s5, s31, 0
	s_lshl_b32 s6, s100, 3
	s_lshl_b32 s2, s101, 3
	s_mov_b32 s9, 0
	s_movk_i32 s3, 0x1000
	s_mov_b32 s10, s100
.LBB0_138:
	s_add_i32 s8, s6, 0xfffff000
	s_cmpk_lt_i32 s10, 0x200
	s_waitcnt lgkmcnt(0)
	s_cselect_b32 s11, s37, s39
	s_cselect_b32 s16, s36, s38
	s_ashr_i32 s7, s6, 31
	s_cmpk_lt_i32 s10, 0x200
	s_cselect_b32 s12, s6, s8
	s_cselect_b32 s13, s7, 0
	s_lshr_b32 s8, s8, 10
	s_mulk_i32 s8, 0x1800
	s_addk_i32 s8, 0x1800
	s_cmpk_lt_i32 s10, 0x200
	v_mov_b32_e32 v0, v234
	s_cselect_b32 s8, 0, s8
	s_lshl_b64 s[14:15], s[8:9], 2
	v_lshlrev_b32_e32 v2, 2, v0
	v_ashrrev_i32_e32 v3, 31, v2
	s_add_u32 s14, s30, s14
	v_lshlrev_b64 v[0:1], 2, v[2:3]
	s_addc_u32 s15, s31, s15
	s_lshl_b64 s[12:13], s[12:13], 12
	v_lshl_add_u64 v[12:13], s[14:15], 0, v[0:1]
	s_add_u32 s12, s16, s12
	s_addc_u32 s13, s11, s13
	v_add_co_u32_e32 v14, vcc, s3, v12
	s_add_i32 s14, s6, 1
	s_nop 0
	v_addc_co_u32_e32 v15, vcc, 0, v13, vcc
	global_load_dwordx4 v[8:11], v[12:13], off
	global_load_dwordx4 v[4:7], v[14:15], off
	v_lshl_add_u64 v[2:3], v[2:3], 1, s[4:5]
	s_add_i32 s14, s6, 0
	s_add_i32 s7, s6, 0xfffff000
	s_ashr_i32 s15, s14, 31
	s_cmpk_lt_i32 s14, 0x1000
	s_cselect_b32 s8, s36, s38
	s_cselect_b32 s13, s15, 0
	s_cselect_b32 s12, s14, s7
	s_cselect_b32 s7, s37, s39
	s_lshl_b64 s[12:13], s[12:13], 12
	s_add_u32 s12, s8, s12
	s_addc_u32 s13, s7, s13
	v_lshl_add_u64 v[18:19], s[12:13], 0, v[0:1]
	global_load_dwordx4 v[20:23], v[18:19], off
	s_add_i32 s14, s6, 1
	s_add_i32 s7, s6, 0xfffff001
	s_ashr_i32 s15, s14, 31
	s_cmpk_lt_i32 s14, 0x1000
	s_cselect_b32 s8, s36, s38
	s_cselect_b32 s13, s15, 0
	s_cselect_b32 s12, s14, s7
	s_cselect_b32 s7, s37, s39
	s_lshl_b64 s[12:13], s[12:13], 12
	s_add_u32 s12, s8, s12
	s_addc_u32 s13, s7, s13
	v_lshl_add_u64 v[18:19], s[12:13], 0, v[0:1]
	global_load_dwordx4 v[24:27], v[18:19], off
	s_add_i32 s14, s6, 2
	s_add_i32 s7, s6, 0xfffff002
	s_ashr_i32 s15, s14, 31
	s_cmpk_lt_i32 s14, 0x1000
	s_cselect_b32 s8, s36, s38
	s_cselect_b32 s13, s15, 0
	s_cselect_b32 s12, s14, s7
	s_cselect_b32 s7, s37, s39
	s_lshl_b64 s[12:13], s[12:13], 12
	s_add_u32 s12, s8, s12
	s_addc_u32 s13, s7, s13
	v_lshl_add_u64 v[18:19], s[12:13], 0, v[0:1]
	global_load_dwordx4 v[28:31], v[18:19], off
	s_add_i32 s14, s6, 3
	s_add_i32 s7, s6, 0xfffff003
	s_ashr_i32 s15, s14, 31
	s_cmpk_lt_i32 s14, 0x1000
	s_cselect_b32 s8, s36, s38
	s_cselect_b32 s13, s15, 0
	s_cselect_b32 s12, s14, s7
	s_cselect_b32 s7, s37, s39
	s_lshl_b64 s[12:13], s[12:13], 12
	s_add_u32 s12, s8, s12
	s_addc_u32 s13, s7, s13
	v_lshl_add_u64 v[18:19], s[12:13], 0, v[0:1]
	global_load_dwordx4 v[32:35], v[18:19], off
	s_add_i32 s14, s6, 4
	s_add_i32 s7, s6, 0xfffff004
	s_ashr_i32 s15, s14, 31
	s_cmpk_lt_i32 s14, 0x1000
	s_cselect_b32 s8, s36, s38
	s_cselect_b32 s13, s15, 0
	s_cselect_b32 s12, s14, s7
	s_cselect_b32 s7, s37, s39
	s_lshl_b64 s[12:13], s[12:13], 12
	s_add_u32 s12, s8, s12
	s_addc_u32 s13, s7, s13
	v_lshl_add_u64 v[18:19], s[12:13], 0, v[0:1]
	global_load_dwordx4 v[36:39], v[18:19], off
	s_add_i32 s14, s6, 5
	s_add_i32 s7, s6, 0xfffff005
	s_ashr_i32 s15, s14, 31
	s_cmpk_lt_i32 s14, 0x1000
	s_cselect_b32 s8, s36, s38
	s_cselect_b32 s13, s15, 0
	s_cselect_b32 s12, s14, s7
	s_cselect_b32 s7, s37, s39
	s_lshl_b64 s[12:13], s[12:13], 12
	s_add_u32 s12, s8, s12
	s_addc_u32 s13, s7, s13
	v_lshl_add_u64 v[18:19], s[12:13], 0, v[0:1]
	global_load_dwordx4 v[40:43], v[18:19], off
	s_add_i32 s14, s6, 6
	s_add_i32 s7, s6, 0xfffff006
	s_ashr_i32 s15, s14, 31
	s_cmpk_lt_i32 s14, 0x1000
	s_cselect_b32 s8, s36, s38
	s_cselect_b32 s13, s15, 0
	s_cselect_b32 s12, s14, s7
	s_cselect_b32 s7, s37, s39
	s_lshl_b64 s[12:13], s[12:13], 12
	s_add_u32 s12, s8, s12
	s_addc_u32 s13, s7, s13
	v_lshl_add_u64 v[18:19], s[12:13], 0, v[0:1]
	global_load_dwordx4 v[44:47], v[18:19], off
	s_add_i32 s14, s6, 7
	s_add_i32 s7, s6, 0xfffff007
	s_ashr_i32 s15, s14, 31
	s_cmpk_lt_i32 s14, 0x1000
	s_cselect_b32 s8, s36, s38
	s_cselect_b32 s13, s15, 0
	s_cselect_b32 s12, s14, s7
	s_cselect_b32 s7, s37, s39
	s_lshl_b64 s[12:13], s[12:13], 12
	s_add_u32 s12, s8, s12
	s_addc_u32 s13, s7, s13
	v_lshl_add_u64 v[18:19], s[12:13], 0, v[0:1]
	global_load_dwordx4 v[48:51], v[18:19], off
	s_waitcnt vmcnt(8)
	v_pk_add_f32 v[4:5], v[4:5], 1.0 op_sel_hi:[1,0]
	v_pk_add_f32 v[6:7], v[6:7], 1.0 op_sel_hi:[1,0]
	v_pk_fma_f32 v[8:9], v[4:5], 0, v[8:9] op_sel_hi:[1,0,1]
	v_pk_fma_f32 v[10:11], v[6:7], 0, v[10:11] op_sel_hi:[1,0,1]
	s_add_i32 s14, s6, 0
	s_ashr_i32 s15, s14, 31
	s_lshl_b64 s[12:13], s[14:15], 11
	v_lshl_add_u64 v[16:17], v[2:3], 0, s[12:13]
	s_waitcnt vmcnt(7)
	v_pk_add_f32 v[20:21], v[20:21], 0 op_sel_hi:[1,0]
	v_pk_add_f32 v[22:23], v[22:23], 0 op_sel_hi:[1,0]
	v_pk_fma_f32 v[20:21], v[20:21], v[4:5], v[8:9]
	v_pk_fma_f32 v[22:23], v[22:23], v[6:7], v[10:11]
	v_cvt_pk_bf16_f32 v20, v20, v21
	v_cvt_pk_bf16_f32 v21, v22, v23
	global_store_dwordx2 v[16:17], v[20:21], off
	s_add_i32 s14, s6, 1
	s_ashr_i32 s15, s14, 31
	s_lshl_b64 s[12:13], s[14:15], 11
	v_lshl_add_u64 v[16:17], v[2:3], 0, s[12:13]
	s_waitcnt vmcnt(6)
	v_pk_add_f32 v[24:25], v[24:25], 0 op_sel_hi:[1,0]
	v_pk_add_f32 v[26:27], v[26:27], 0 op_sel_hi:[1,0]
	v_pk_fma_f32 v[24:25], v[24:25], v[4:5], v[8:9]
	v_pk_fma_f32 v[26:27], v[26:27], v[6:7], v[10:11]
	v_cvt_pk_bf16_f32 v24, v24, v25
	v_cvt_pk_bf16_f32 v25, v26, v27
	global_store_dwordx2 v[16:17], v[24:25], off
	s_add_i32 s14, s6, 2
	s_ashr_i32 s15, s14, 31
	s_lshl_b64 s[12:13], s[14:15], 11
	v_lshl_add_u64 v[16:17], v[2:3], 0, s[12:13]
	s_waitcnt vmcnt(5)
	v_pk_add_f32 v[28:29], v[28:29], 0 op_sel_hi:[1,0]
	v_pk_add_f32 v[30:31], v[30:31], 0 op_sel_hi:[1,0]
	v_pk_fma_f32 v[28:29], v[28:29], v[4:5], v[8:9]
	v_pk_fma_f32 v[30:31], v[30:31], v[6:7], v[10:11]
	v_cvt_pk_bf16_f32 v28, v28, v29
	v_cvt_pk_bf16_f32 v29, v30, v31
	global_store_dwordx2 v[16:17], v[28:29], off
	s_add_i32 s14, s6, 3
	s_ashr_i32 s15, s14, 31
	s_lshl_b64 s[12:13], s[14:15], 11
	v_lshl_add_u64 v[16:17], v[2:3], 0, s[12:13]
	s_waitcnt vmcnt(4)
	v_pk_add_f32 v[32:33], v[32:33], 0 op_sel_hi:[1,0]
	v_pk_add_f32 v[34:35], v[34:35], 0 op_sel_hi:[1,0]
	v_pk_fma_f32 v[32:33], v[32:33], v[4:5], v[8:9]
	v_pk_fma_f32 v[34:35], v[34:35], v[6:7], v[10:11]
	v_cvt_pk_bf16_f32 v32, v32, v33
	v_cvt_pk_bf16_f32 v33, v34, v35
	global_store_dwordx2 v[16:17], v[32:33], off
	s_add_i32 s14, s6, 4
	s_ashr_i32 s15, s14, 31
	s_lshl_b64 s[12:13], s[14:15], 11
	v_lshl_add_u64 v[16:17], v[2:3], 0, s[12:13]
	s_waitcnt vmcnt(3)
	v_pk_add_f32 v[36:37], v[36:37], 0 op_sel_hi:[1,0]
	v_pk_add_f32 v[38:39], v[38:39], 0 op_sel_hi:[1,0]
	v_pk_fma_f32 v[36:37], v[36:37], v[4:5], v[8:9]
	v_pk_fma_f32 v[38:39], v[38:39], v[6:7], v[10:11]
	v_cvt_pk_bf16_f32 v36, v36, v37
	v_cvt_pk_bf16_f32 v37, v38, v39
	global_store_dwordx2 v[16:17], v[36:37], off
	s_add_i32 s14, s6, 5
	s_ashr_i32 s15, s14, 31
	s_lshl_b64 s[12:13], s[14:15], 11
	v_lshl_add_u64 v[16:17], v[2:3], 0, s[12:13]
	s_waitcnt vmcnt(2)
	v_pk_add_f32 v[40:41], v[40:41], 0 op_sel_hi:[1,0]
	v_pk_add_f32 v[42:43], v[42:43], 0 op_sel_hi:[1,0]
	v_pk_fma_f32 v[40:41], v[40:41], v[4:5], v[8:9]
	v_pk_fma_f32 v[42:43], v[42:43], v[6:7], v[10:11]
	v_cvt_pk_bf16_f32 v40, v40, v41
	v_cvt_pk_bf16_f32 v41, v42, v43
	global_store_dwordx2 v[16:17], v[40:41], off
	s_add_i32 s14, s6, 6
	s_ashr_i32 s15, s14, 31
	s_lshl_b64 s[12:13], s[14:15], 11
	v_lshl_add_u64 v[16:17], v[2:3], 0, s[12:13]
	s_waitcnt vmcnt(1)
	v_pk_add_f32 v[44:45], v[44:45], 0 op_sel_hi:[1,0]
	v_pk_add_f32 v[46:47], v[46:47], 0 op_sel_hi:[1,0]
	v_pk_fma_f32 v[44:45], v[44:45], v[4:5], v[8:9]
	v_pk_fma_f32 v[46:47], v[46:47], v[6:7], v[10:11]
	v_cvt_pk_bf16_f32 v44, v44, v45
	v_cvt_pk_bf16_f32 v45, v46, v47
	global_store_dwordx2 v[16:17], v[44:45], off
	s_add_i32 s14, s6, 7
	s_ashr_i32 s15, s14, 31
	s_lshl_b64 s[12:13], s[14:15], 11
	v_lshl_add_u64 v[16:17], v[2:3], 0, s[12:13]
	s_waitcnt vmcnt(0)
	v_pk_add_f32 v[48:49], v[48:49], 0 op_sel_hi:[1,0]
	v_pk_add_f32 v[50:51], v[50:51], 0 op_sel_hi:[1,0]
	v_pk_fma_f32 v[48:49], v[48:49], v[4:5], v[8:9]
	v_pk_fma_f32 v[50:51], v[50:51], v[6:7], v[10:11]
	v_cvt_pk_bf16_f32 v48, v48, v49
	v_cvt_pk_bf16_f32 v49, v50, v51
	global_store_dwordx2 v[16:17], v[48:49], off
	s_add_i32 s10, s10, s101
	s_add_i32 s6, s6, s2
	s_cmp_gt_i32 s10, s99
	s_cbranch_scc0 .LBB0_138
.LBB0_139:
	s_cmp_gt_u32 s67, 2
	s_cbranch_scc0 .LBB0_189
	s_waitcnt vmcnt(0)
	s_waitcnt vmcnt(63) expcnt(7) lgkmcnt(15)
	s_barrier
	s_mov_b64 s[4:5], exec
	v_readlane_b32 s2, v251, 3
	v_readlane_b32 s3, v251, 4
	s_and_b64 s[2:3], s[4:5], s[2:3]
	s_mov_b64 exec, s[2:3]
	s_cbranch_execz .Lxb_done_2
	v_mov_b32_e32 v0, 0
	s_waitcnt vmcnt(0) expcnt(0) lgkmcnt(0)
	ds_read_b32 v2, v0
	ds_read_b32 v1, v0 offset:4
	v_readlane_b32 s0, v251, 2
	v_readlane_b32 s6, v251, 5
	v_readlane_b32 s7, v251, 6
	s_lshl_b32 s0, s0, 8
	s_add_u32 s8, s6, s0
	s_addc_u32 s9, s7, 0
	v_mov_b32_e32 v3, 1
	v_mov_b32_e32 v4, 0x1000
	s_nop 4
	global_atomic_add v3, v4, v3, s[8:9] offset:1024 sc0
	buffer_inv sc1
	s_sub_u32 s10, 1, s66
	s_add_u32 s11, s10, 1
	s_waitcnt lgkmcnt(0)
	v_readfirstlane_b32 s12, v2
	v_readfirstlane_b32 s13, v1
	s_mul_i32 s14, s12, s11
	s_mul_i32 s15, s13, s11
	s_waitcnt vmcnt(0)
	v_readfirstlane_b32 s16, v3
	s_add_u32 s16, s16, 1
	s_cmp_lg_u32 s16, s14
	s_cbranch_scc1 .Lxb_wait_2
	s_waitcnt vmcnt(0)
	v_mov_b32_e32 v3, 1
	v_mov_b32_e32 v4, 0x7f000
	global_atomic_add v3, v4, v3, s[30:31] offset:1024 sc0
	s_waitcnt vmcnt(0)
	v_mov_b32_e32 v3, 1
	v_mov_b32_e32 v4, s0
	v_add_u32_e32 v4, 0x2400, v4
	global_atomic_add v4, v3, s[6:7]

.LBB0_1762:
	v_readlane_b32 s66, v251, 55
	v_readlane_b32 s67, v251, 56
	s_cmp_gt_i32 s67, 6
	s_cbranch_scc0 .LBB0_1812
	s_waitcnt vmcnt(0)
	s_waitcnt vmcnt(63) expcnt(7) lgkmcnt(15)
	s_barrier
	s_mov_b64 s[4:5], exec
	v_readlane_b32 s2, v251, 3
	v_readlane_b32 s3, v251, 4
	s_and_b64 s[2:3], s[4:5], s[2:3]
	s_mov_b64 exec, s[2:3]
	s_cbranch_execz .Lxb_done_6
	v_mov_b32_e32 v0, 0
	s_waitcnt vmcnt(0) expcnt(0) lgkmcnt(0)
	ds_read_b32 v2, v0
	ds_read_b32 v1, v0 offset:4
	v_readlane_b32 s0, v251, 2
	v_readlane_b32 s6, v251, 5
	v_readlane_b32 s7, v251, 6
	s_lshl_b32 s0, s0, 8
	s_add_u32 s8, s6, s0
	s_addc_u32 s9, s7, 0
	v_mov_b32_e32 v3, 1
	v_mov_b32_e32 v4, 0x1000
	s_nop 4
	global_atomic_add v3, v4, v3, s[8:9] offset:1024 sc0
	buffer_inv sc1
	s_sub_u32 s10, 5, s66
	s_add_u32 s11, s10, 1
	s_waitcnt lgkmcnt(0)
	v_readfirstlane_b32 s12, v2
	v_readfirstlane_b32 s13, v1
	s_mul_i32 s14, s12, s11
	s_mul_i32 s15, s13, s11
	s_waitcnt vmcnt(0)
	v_readfirstlane_b32 s16, v3
	s_add_u32 s16, s16, 1
	s_cmp_lg_u32 s16, s14
	s_cbranch_scc1 .Lxb_wait_6
	s_waitcnt vmcnt(0)
	v_mov_b32_e32 v3, 1
	v_mov_b32_e32 v4, 0x7f000
	global_atomic_add v3, v4, v3, s[30:31] offset:1024 sc0
	s_waitcnt vmcnt(0)
	v_mov_b32_e32 v3, 1
	v_mov_b32_e32 v4, s0
	v_add_u32_e32 v4, 0x2400, v4
	global_atomic_add v4, v3, s[6:7]

.LBB0_1828:
	s_cmp_gt_i32 s67, 7
	s_cbranch_scc0 .LBB0_1878
	s_waitcnt vmcnt(0)
	s_waitcnt vmcnt(63) expcnt(7) lgkmcnt(15)
	s_barrier
	s_mov_b64 s[4:5], exec
	v_readlane_b32 s2, v251, 3
	v_readlane_b32 s3, v251, 4
	s_and_b64 s[2:3], s[4:5], s[2:3]
	s_mov_b64 exec, s[2:3]
	s_cbranch_execz .Lxb_done_7
	v_mov_b32_e32 v0, 0
	s_waitcnt vmcnt(0) expcnt(0) lgkmcnt(0)
	ds_read_b32 v2, v0
	ds_read_b32 v1, v0 offset:4
	v_readlane_b32 s0, v251, 2
	v_readlane_b32 s6, v251, 5
	v_readlane_b32 s7, v251, 6
	s_lshl_b32 s0, s0, 8
	s_add_u32 s8, s6, s0
	s_addc_u32 s9, s7, 0
	v_mov_b32_e32 v3, 1
	v_mov_b32_e32 v4, 0x1000
	s_nop 4
	global_atomic_add v3, v4, v3, s[8:9] offset:1024 sc0
	buffer_inv sc1
	s_sub_u32 s10, 6, s66
	s_add_u32 s11, s10, 1
	s_waitcnt lgkmcnt(0)
	v_readfirstlane_b32 s12, v2
	v_readfirstlane_b32 s13, v1
	s_mul_i32 s14, s12, s11
	s_mul_i32 s15, s13, s11
	s_waitcnt vmcnt(0)
	v_readfirstlane_b32 s16, v3
	s_add_u32 s16, s16, 1
	s_cmp_lg_u32 s16, s14
	s_cbranch_scc1 .Lxb_wait_7
	s_waitcnt vmcnt(0)
	v_mov_b32_e32 v3, 1
	v_mov_b32_e32 v4, 0x7f000
	global_atomic_add v3, v4, v3, s[30:31] offset:1024 sc0
	s_waitcnt vmcnt(0)
	v_mov_b32_e32 v3, 1
	v_mov_b32_e32 v4, s0
	v_add_u32_e32 v4, 0x2400, v4
	global_atomic_add v4, v3, s[6:7]

.LBB0_1878:
	s_cmp_gt_i32 s66, 7
	s_cselect_b64 s[0:1], -1, 0
	s_cmp_lt_i32 s67, 8
	s_cselect_b64 s[2:3], -1, 0
	s_or_b64 s[0:1], s[0:1], s[2:3]
	s_and_b64 vcc, exec, s[0:1]
	s_cbranch_vccnz .LBB0_1932
	v_readlane_b32 s36, v250, 6
	s_cmpk_gt_i32 s78, 0x3ff
	v_readlane_b32 s37, v250, 7
	v_readlane_b32 s38, v250, 8
	v_readlane_b32 s39, v250, 9
	v_readlane_b32 s40, v250, 10
	v_readlane_b32 s41, v250, 11
	v_readlane_b32 s42, v250, 12
	v_readlane_b32 s43, v250, 13
	v_readlane_b32 s44, v250, 14
	v_readlane_b32 s45, v250, 15
	v_readlane_b32 s46, v250, 16
	v_readlane_b32 s47, v250, 17
	v_readlane_b32 s48, v250, 18
	v_readlane_b32 s49, v250, 19
	v_readlane_b32 s50, v250, 20
	v_readlane_b32 s51, v250, 21
	s_cbranch_scc1 .LBB0_1882
	s_mov_b32 s100, s78
	s_mov_b32 s101, s64
	s_movk_i32 s99, 0x3ff
	s_cmpk_eq_i32 s64, 0x200
	s_cbranch_scc0 .Lhm_nomap_2
	s_and_b32 s99, s78, 7
	s_lshl_b32 s99, s99, 7
	s_lshr_b32 s100, s78, 3
	s_add_i32 s100, s100, s99
	s_add_i32 s99, s99, 0x7f
	s_movk_i32 s101, 64
.Lhm_nomap_2:
	s_add_u32 s2, s30, 0x3c000
	s_addc_u32 s3, s31, 0
	s_add_u32 s0, s30, 0xab93e00
	s_addc_u32 s1, s31, 0
	s_add_u32 s11, s30, 0xd793e00
	s_addc_u32 s14, s31, 0
	s_lshl_b32 s4, s100, 4
	s_lshl_b32 s5, s100, 3
	s_or_b32 s4, s4, 14
	s_lshl_b32 s15, s101, 4
	s_or_b32 s6, s5, 7
	s_lshl_b32 s16, s101, 3
	s_mov_b32 s9, 0
	s_waitcnt vmcnt(11)
	v_mov_b32_e32 v12, 0
	s_mov_b32 s10, 0x3a800000
	s_mov_b32 s17, 0x800000
	s_movk_i32 s18, 0x4000
	s_movk_i32 s19, 0x3000
	s_mov_b32 s20, s100
.LBB0_1881:
	s_add_i32 s5, s6, 0xffffeff9
	s_lshr_b32 s5, s5, 10
	s_mulk_i32 s5, 0x1800
	s_add_i32 s12, s6, -7
	s_addk_i32 s5, 0x1800
	v_mov_b32_e32 v0, v234
	s_cmpk_gt_i32 s20, 0x1ff
	s_cselect_b32 s8, s5, 0
	v_lshlrev_b32_e32 v2, 2, v0
	v_ashrrev_i32_e32 v3, 31, v2
	s_lshl_b64 s[22:23], s[8:9], 2
	v_lshlrev_b64 v[0:1], 2, v[2:3]
	s_add_u32 s22, s30, s22
	v_lshl_add_u64 v[4:5], s[36:37], 0, v[0:1]
	s_addc_u32 s23, s31, s23
	v_lshl_add_u64 v[10:11], s[38:39], 0, v[0:1]
	global_load_dwordx4 v[6:9], v[4:5], off
	global_load_dwordx4 v[14:17], v[10:11], off
	s_ashr_i32 s13, s12, 31
	v_lshl_add_u64 v[4:5], s[22:23], 0, v[0:1]
	s_lshl_b64 s[22:23], s[12:13], 12
	v_add_co_u32_e32 v10, vcc, s18, v4
	s_add_u32 s22, s11, s22
	s_nop 0
	v_addc_co_u32_e32 v11, vcc, 0, v5, vcc
	v_add_co_u32_e32 v4, vcc, s19, v4
	s_addc_u32 s23, s14, s23
	s_add_i32 s24, s4, -14
	v_addc_co_u32_e32 v5, vcc, 0, v5, vcc
	s_ashr_i32 s25, s24, 31
	global_load_dwordx4 v[18:21], v[10:11], off
	global_load_dwordx4 v[22:25], v[4:5], off
	v_lshl_add_u64 v[4:5], s[22:23], 0, v[0:1]
	s_lshl_b64 s[22:23], s[24:25], 2
	s_add_u32 s22, s2, s22
	s_addc_u32 s23, s3, s23
	global_load_dwordx2 v[30:31], v12, s[22:23]
	s_waitcnt lgkmcnt(0)
	global_load_dwordx4 v[26:29], v[4:5], off
	s_add_i32 s22, s6, -6
	v_lshl_add_u64 v[2:3], v[2:3], 1, s[0:1]
	s_lshl_b64 s[12:13], s[12:13], 11
	s_ashr_i32 s23, s22, 31
	s_waitcnt vmcnt(12)
	v_lshl_add_u64 v[32:33], v[2:3], 0, s[12:13]
	s_lshl_b64 s[12:13], s[22:23], 12
	s_add_u32 s12, s11, s12
	s_addc_u32 s13, s14, s13
	s_add_i32 s24, s4, -12
	s_ashr_i32 s25, s24, 31
	s_waitcnt vmcnt(11)
	v_lshl_add_u64 v[34:35], s[12:13], 0, v[0:1]
	s_lshl_b64 s[12:13], s[24:25], 2
	s_add_u32 s12, s2, s12
	s_addc_u32 s13, s3, s13
	s_waitcnt vmcnt(3)
	v_pk_add_f32 v[10:11], v[18:19], 1.0 op_sel_hi:[1,0]
	s_nop 0
	v_pk_mul_f32 v[4:5], v[10:11], v[6:7]
	s_waitcnt vmcnt(2)
	v_pk_fma_f32 v[6:7], v[14:15], v[10:11], v[22:23]
	v_pk_add_f32 v[18:19], v[20:21], 1.0 op_sel_hi:[1,0]
	s_waitcnt vmcnt(1)
	v_pk_mul_f32 v[14:15], v[30:31], s[10:11] op_sel_hi:[1,0]
	s_nop 0
	v_fma_f32 v13, -v14, v14, v15
	v_max_f32_e32 v13, 0, v13
	v_add_f32_e32 v13, 0x3727c5ac, v13
	v_mul_f32_e32 v15, 0x4b800000, v13
	v_cmp_gt_f32_e32 vcc, s17, v13
	v_pk_fma_f32 v[10:11], v[16:17], v[18:19], v[24:25]
	v_pk_mul_f32 v[8:9], v[18:19], v[8:9]
	v_cndmask_b32_e32 v13, v13, v15, vcc
	v_rsq_f32_e32 v13, v13
	s_nop 0
	v_mul_f32_e32 v15, 0x45800000, v13
	v_cndmask_b32_e32 v16, v13, v15, vcc
	v_mul_f32_e64 v14, v16, -v14
	s_waitcnt vmcnt(0)
	v_pk_fma_f32 v[18:19], v[26:27], v[16:17], v[14:15] op_sel_hi:[1,0,0]
	v_pk_fma_f32 v[14:15], v[28:29], v[16:17], v[14:15] op_sel_hi:[1,0,0]
	v_pk_fma_f32 v[16:17], v[18:19], v[4:5], v[6:7]
	v_pk_fma_f32 v[14:15], v[14:15], v[8:9], v[10:11]
	v_cvt_pk_bf16_f32 v16, v16, v17
	v_cvt_pk_bf16_f32 v17, v14, v15
	global_store_dwordx2 v[32:33], v[16:17], off
	global_load_dwordx2 v[18:19], v12, s[12:13]
	s_nop 0
	global_load_dwordx4 v[14:17], v[34:35], off
	s_lshl_b64 s[12:13], s[22:23], 11
	s_add_i32 s22, s6, -5
	s_ashr_i32 s23, s22, 31
	v_lshl_add_u64 v[20:21], v[2:3], 0, s[12:13]
	s_lshl_b64 s[12:13], s[22:23], 12
	s_add_u32 s12, s11, s12
	s_addc_u32 s13, s14, s13
	s_add_i32 s24, s4, -10
	s_ashr_i32 s25, s24, 31
	v_lshl_add_u64 v[22:23], s[12:13], 0, v[0:1]
	s_lshl_b64 s[12:13], s[24:25], 2
	s_add_u32 s12, s2, s12
	s_addc_u32 s13, s3, s13
	s_waitcnt vmcnt(1)
	v_pk_mul_f32 v[18:19], v[18:19], s[10:11] op_sel_hi:[1,0]
	s_nop 0
	v_fma_f32 v13, -v18, v18, v19
	v_max_f32_e32 v13, 0, v13
	v_add_f32_e32 v13, 0x3727c5ac, v13
	v_mul_f32_e32 v19, 0x4b800000, v13
	v_cmp_gt_f32_e32 vcc, s17, v13
	s_nop 1
	v_cndmask_b32_e32 v13, v13, v19, vcc
	v_rsq_f32_e32 v13, v13
	s_nop 0
	v_mul_f32_e32 v19, 0x45800000, v13
	v_cndmask_b32_e32 v24, v13, v19, vcc
	v_mul_f32_e64 v18, v24, -v18
	s_waitcnt vmcnt(0)
	v_pk_fma_f32 v[14:15], v[14:15], v[24:25], v[18:19] op_sel_hi:[1,0,0]
	v_pk_fma_f32 v[16:17], v[16:17], v[24:25], v[18:19] op_sel_hi:[1,0,0]
	v_pk_fma_f32 v[14:15], v[14:15], v[4:5], v[6:7]
	v_pk_fma_f32 v[16:17], v[16:17], v[8:9], v[10:11]
	v_cvt_pk_bf16_f32 v14, v14, v15
	v_cvt_pk_bf16_f32 v15, v16, v17
	global_store_dwordx2 v[20:21], v[14:15], off
	global_load_dwordx2 v[18:19], v12, s[12:13]
	s_nop 0
	global_load_dwordx4 v[14:17], v[22:23], off
	s_lshl_b64 s[12:13], s[22:23], 11
	s_add_i32 s22, s6, -4
	s_ashr_i32 s23, s22, 31
	v_lshl_add_u64 v[20:21], v[2:3], 0, s[12:13]
	s_lshl_b64 s[12:13], s[22:23], 12
	s_add_u32 s12, s11, s12
	s_addc_u32 s13, s14, s13
	s_add_i32 s24, s4, -8
	s_ashr_i32 s25, s24, 31
	v_lshl_add_u64 v[22:23], s[12:13], 0, v[0:1]
	s_lshl_b64 s[12:13], s[24:25], 2
	s_add_u32 s12, s2, s12
	s_addc_u32 s13, s3, s13
	s_waitcnt vmcnt(1)
	v_pk_mul_f32 v[18:19], v[18:19], s[10:11] op_sel_hi:[1,0]
	s_nop 0
	v_fma_f32 v13, -v18, v18, v19
	v_max_f32_e32 v13, 0, v13
	v_add_f32_e32 v13, 0x3727c5ac, v13
	v_mul_f32_e32 v19, 0x4b800000, v13
	v_cmp_gt_f32_e32 vcc, s17, v13
	s_nop 1
	v_cndmask_b32_e32 v13, v13, v19, vcc
	v_rsq_f32_e32 v13, v13
	s_nop 0
	v_mul_f32_e32 v19, 0x45800000, v13
	v_cndmask_b32_e32 v24, v13, v19, vcc
	v_mul_f32_e64 v18, v24, -v18
	s_waitcnt vmcnt(0)
	v_pk_fma_f32 v[14:15], v[14:15], v[24:25], v[18:19] op_sel_hi:[1,0,0]
	v_pk_fma_f32 v[16:17], v[16:17], v[24:25], v[18:19] op_sel_hi:[1,0,0]
	v_pk_fma_f32 v[14:15], v[14:15], v[4:5], v[6:7]
	v_pk_fma_f32 v[16:17], v[16:17], v[8:9], v[10:11]
	v_cvt_pk_bf16_f32 v14, v14, v15
	v_cvt_pk_bf16_f32 v15, v16, v17
	global_store_dwordx2 v[20:21], v[14:15], off
	global_load_dwordx2 v[18:19], v12, s[12:13]
	s_nop 0
	global_load_dwordx4 v[14:17], v[22:23], off
	s_lshl_b64 s[12:13], s[22:23], 11
	s_add_i32 s22, s6, -3
	s_ashr_i32 s23, s22, 31
	v_lshl_add_u64 v[20:21], v[2:3], 0, s[12:13]
	s_lshl_b64 s[12:13], s[22:23], 12
	s_add_u32 s12, s11, s12
	s_addc_u32 s13, s14, s13
	s_add_i32 s24, s4, -6
	s_ashr_i32 s25, s24, 31
	v_lshl_add_u64 v[22:23], s[12:13], 0, v[0:1]
	s_lshl_b64 s[12:13], s[24:25], 2
	s_add_u32 s12, s2, s12
	s_addc_u32 s13, s3, s13
	s_waitcnt vmcnt(1)
	v_pk_mul_f32 v[18:19], v[18:19], s[10:11] op_sel_hi:[1,0]
	s_nop 0
	v_fma_f32 v13, -v18, v18, v19
	v_max_f32_e32 v13, 0, v13
	v_add_f32_e32 v13, 0x3727c5ac, v13
	v_mul_f32_e32 v19, 0x4b800000, v13
	v_cmp_gt_f32_e32 vcc, s17, v13
	s_nop 1
	v_cndmask_b32_e32 v13, v13, v19, vcc
	v_rsq_f32_e32 v13, v13
	s_nop 0
	v_mul_f32_e32 v19, 0x45800000, v13
	v_cndmask_b32_e32 v24, v13, v19, vcc
	v_mul_f32_e64 v18, v24, -v18
	s_waitcnt vmcnt(0)
	v_pk_fma_f32 v[14:15], v[14:15], v[24:25], v[18:19] op_sel_hi:[1,0,0]
	v_pk_fma_f32 v[16:17], v[16:17], v[24:25], v[18:19] op_sel_hi:[1,0,0]
	v_pk_fma_f32 v[14:15], v[14:15], v[4:5], v[6:7]
	v_pk_fma_f32 v[16:17], v[16:17], v[8:9], v[10:11]
	v_cvt_pk_bf16_f32 v14, v14, v15
	v_cvt_pk_bf16_f32 v15, v16, v17
	global_store_dwordx2 v[20:21], v[14:15], off
	global_load_dwordx2 v[18:19], v12, s[12:13]
	s_nop 0
	global_load_dwordx4 v[14:17], v[22:23], off
	s_lshl_b64 s[12:13], s[22:23], 11
	s_add_i32 s22, s6, -2
	s_ashr_i32 s23, s22, 31
	v_lshl_add_u64 v[20:21], v[2:3], 0, s[12:13]
	s_lshl_b64 s[12:13], s[22:23], 12
	s_add_u32 s12, s11, s12
	s_addc_u32 s13, s14, s13
	s_add_i32 s24, s4, -4
	s_ashr_i32 s25, s24, 31
	s_lshl_b64 s[24:25], s[24:25], 2
	s_add_u32 s24, s2, s24
	s_addc_u32 s25, s3, s25
	s_waitcnt vmcnt(1)
	v_pk_mul_f32 v[18:19], v[18:19], s[10:11] op_sel_hi:[1,0]
	s_nop 0
	v_fma_f32 v13, -v18, v18, v19
	v_max_f32_e32 v13, 0, v13
	v_add_f32_e32 v13, 0x3727c5ac, v13
	v_mul_f32_e32 v19, 0x4b800000, v13
	v_cmp_gt_f32_e32 vcc, s17, v13
	s_nop 1
	v_cndmask_b32_e32 v13, v13, v19, vcc
	v_rsq_f32_e32 v13, v13
	s_nop 0
	v_mul_f32_e32 v19, 0x45800000, v13
	v_cndmask_b32_e32 v22, v13, v19, vcc
	v_mul_f32_e64 v18, v22, -v18
	s_waitcnt vmcnt(0)
	v_pk_fma_f32 v[14:15], v[14:15], v[22:23], v[18:19] op_sel_hi:[1,0,0]
	v_pk_fma_f32 v[16:17], v[16:17], v[22:23], v[18:19] op_sel_hi:[1,0,0]
	v_pk_fma_f32 v[14:15], v[14:15], v[4:5], v[6:7]
	v_pk_fma_f32 v[16:17], v[16:17], v[8:9], v[10:11]
	v_cvt_pk_bf16_f32 v14, v14, v15
	v_cvt_pk_bf16_f32 v15, v16, v17
	global_store_dwordx2 v[20:21], v[14:15], off
	global_load_dwordx2 v[18:19], v12, s[24:25]
	v_lshl_add_u64 v[14:15], s[12:13], 0, v[0:1]
	global_load_dwordx4 v[14:17], v[14:15], off
	s_lshl_b64 s[12:13], s[22:23], 11
	s_add_i32 s22, s6, -1
	s_ashr_i32 s23, s22, 31
	v_lshl_add_u64 v[20:21], v[2:3], 0, s[12:13]
	s_lshl_b64 s[12:13], s[22:23], 12
	s_add_u32 s12, s11, s12
	s_addc_u32 s13, s14, s13
	s_add_i32 s24, s4, -2
	s_ashr_i32 s25, s24, 31
	s_lshl_b64 s[24:25], s[24:25], 2
	s_add_u32 s24, s2, s24
	s_addc_u32 s25, s3, s25
	s_ashr_i32 s5, s4, 31
	s_ashr_i32 s7, s6, 31
	s_waitcnt vmcnt(1)
	v_pk_mul_f32 v[18:19], v[18:19], s[10:11] op_sel_hi:[1,0]
	s_nop 0
	v_fma_f32 v13, -v18, v18, v19
	v_max_f32_e32 v13, 0, v13
	v_add_f32_e32 v13, 0x3727c5ac, v13
	v_mul_f32_e32 v19, 0x4b800000, v13
	v_cmp_gt_f32_e32 vcc, s17, v13
	s_nop 1
	v_cndmask_b32_e32 v13, v13, v19, vcc
	v_rsq_f32_e32 v13, v13
	s_nop 0
	v_mul_f32_e32 v19, 0x45800000, v13
	v_cndmask_b32_e32 v22, v13, v19, vcc
	v_mul_f32_e64 v18, v22, -v18
	s_waitcnt vmcnt(0)
	v_pk_fma_f32 v[14:15], v[14:15], v[22:23], v[18:19] op_sel_hi:[1,0,0]
	v_pk_fma_f32 v[16:17], v[16:17], v[22:23], v[18:19] op_sel_hi:[1,0,0]
	v_pk_fma_f32 v[14:15], v[14:15], v[4:5], v[6:7]
	v_pk_fma_f32 v[16:17], v[16:17], v[8:9], v[10:11]
	v_cvt_pk_bf16_f32 v14, v14, v15
	v_cvt_pk_bf16_f32 v15, v16, v17
	global_store_dwordx2 v[20:21], v[14:15], off
	global_load_dwordx2 v[18:19], v12, s[24:25]
	v_lshl_add_u64 v[14:15], s[12:13], 0, v[0:1]
	global_load_dwordx4 v[14:17], v[14:15], off
	s_lshl_b64 s[12:13], s[22:23], 11
	v_lshl_add_u64 v[20:21], v[2:3], 0, s[12:13]
	s_lshl_b64 s[12:13], s[4:5], 2
	s_add_u32 s12, s2, s12
	s_addc_u32 s13, s3, s13
	s_waitcnt vmcnt(1)
	v_pk_mul_f32 v[18:19], v[18:19], s[10:11] op_sel_hi:[1,0]
	s_nop 0
	v_fma_f32 v13, -v18, v18, v19
	v_max_f32_e32 v13, 0, v13
	v_add_f32_e32 v13, 0x3727c5ac, v13
	v_mul_f32_e32 v19, 0x4b800000, v13
	v_cmp_gt_f32_e32 vcc, s17, v13
	s_nop 1
	v_cndmask_b32_e32 v13, v13, v19, vcc
	v_rsq_f32_e32 v13, v13
	s_nop 0
	v_mul_f32_e32 v19, 0x45800000, v13
	v_cndmask_b32_e32 v22, v13, v19, vcc
	v_mul_f32_e64 v18, v22, -v18
	s_waitcnt vmcnt(0)
	v_pk_fma_f32 v[14:15], v[14:15], v[22:23], v[18:19] op_sel_hi:[1,0,0]
	v_pk_fma_f32 v[16:17], v[16:17], v[22:23], v[18:19] op_sel_hi:[1,0,0]
	v_pk_fma_f32 v[14:15], v[14:15], v[4:5], v[6:7]
	v_pk_fma_f32 v[16:17], v[16:17], v[8:9], v[10:11]
	v_cvt_pk_bf16_f32 v14, v14, v15
	v_cvt_pk_bf16_f32 v15, v16, v17
	global_store_dwordx2 v[20:21], v[14:15], off
	global_load_dwordx2 v[18:19], v12, s[12:13]
	s_lshl_b64 s[12:13], s[6:7], 12
	s_add_u32 s12, s11, s12
	s_addc_u32 s13, s14, s13
	v_lshl_add_u64 v[0:1], s[12:13], 0, v[0:1]
	global_load_dwordx4 v[14:17], v[0:1], off
	s_lshl_b64 s[12:13], s[6:7], 11
	v_lshl_add_u64 v[0:1], v[2:3], 0, s[12:13]
	s_add_i32 s20, s20, s101
	s_add_i32 s4, s4, s15
	s_add_i32 s6, s6, s16
	s_cmp_gt_i32 s20, s99
	s_waitcnt vmcnt(1)
	v_pk_mul_f32 v[2:3], v[18:19], s[10:11] op_sel_hi:[1,0]
	s_nop 0
	v_fma_f32 v3, -v2, v2, v3
	v_max_f32_e32 v3, 0, v3
	v_add_f32_e32 v3, 0x3727c5ac, v3
	v_mul_f32_e32 v13, 0x4b800000, v3
	v_cmp_gt_f32_e32 vcc, s17, v3
	s_nop 1
	v_cndmask_b32_e32 v3, v3, v13, vcc
	v_rsq_f32_e32 v3, v3
	s_nop 0
	v_mul_f32_e32 v13, 0x45800000, v3
	v_cndmask_b32_e32 v18, v3, v13, vcc
	v_mul_f32_e64 v2, v18, -v2
	s_waitcnt vmcnt(0)
	v_pk_fma_f32 v[14:15], v[14:15], v[18:19], v[2:3] op_sel_hi:[1,0,0]
	v_pk_fma_f32 v[2:3], v[16:17], v[18:19], v[2:3] op_sel_hi:[1,0,0]
	v_pk_fma_f32 v[4:5], v[14:15], v[4:5], v[6:7]
	v_pk_fma_f32 v[2:3], v[2:3], v[8:9], v[10:11]
	v_cvt_pk_bf16_f32 v4, v4, v5
	v_cvt_pk_bf16_f32 v5, v2, v3
	global_store_dwordx2 v[0:1], v[4:5], off
	s_cbranch_scc0 .LBB0_1881
.LBB0_1882:
	s_cmp_gt_u32 s67, 8
	s_cbranch_scc0 .LBB0_1932
	s_waitcnt vmcnt(0)
	s_waitcnt vmcnt(63) expcnt(7) lgkmcnt(15)
	s_barrier
	s_mov_b64 s[4:5], exec
	v_readlane_b32 s2, v251, 3
	v_readlane_b32 s3, v251, 4
	s_and_b64 s[2:3], s[4:5], s[2:3]
	s_mov_b64 exec, s[2:3]
	s_cbranch_execz .Lxb_done_8
	v_mov_b32_e32 v0, 0
	s_waitcnt vmcnt(0) expcnt(0) lgkmcnt(0)
	ds_read_b32 v2, v0
	ds_read_b32 v1, v0 offset:4
	v_readlane_b32 s0, v251, 2
	v_readlane_b32 s6, v251, 5
	v_readlane_b32 s7, v251, 6
	s_lshl_b32 s0, s0, 8
	s_add_u32 s8, s6, s0
	s_addc_u32 s9, s7, 0
	v_mov_b32_e32 v3, 1
	v_mov_b32_e32 v4, 0x1000
	s_nop 4
	global_atomic_add v3, v4, v3, s[8:9] offset:1024 sc0
	buffer_inv sc1
	s_sub_u32 s10, 7, s66
	s_add_u32 s11, s10, 1
	s_waitcnt lgkmcnt(0)
	v_readfirstlane_b32 s12, v2
	v_readfirstlane_b32 s13, v1
	s_mul_i32 s14, s12, s11
	s_mul_i32 s15, s13, s11
	s_waitcnt vmcnt(0)
	v_readfirstlane_b32 s16, v3
	s_add_u32 s16, s16, 1
	s_cmp_lg_u32 s16, s14
	s_cbranch_scc1 .Lxb_wait_8
	s_waitcnt vmcnt(0)
	v_mov_b32_e32 v3, 1
	v_mov_b32_e32 v4, 0x7f000
	global_atomic_add v3, v4, v3, s[30:31] offset:1024 sc0
	s_waitcnt vmcnt(0)
	v_mov_b32_e32 v3, 1
	v_mov_b32_e32 v4, s0
	v_add_u32_e32 v4, 0x2400, v4
	global_atomic_add v4, v3, s[6:7]

.Lcv_ret_p4:
	s_mov_b32 s101, 0
	s_cmp_gt_i32 s67, 9
	s_cbranch_scc0 .LBB0_1992
	s_waitcnt vmcnt(0)
	s_waitcnt vmcnt(63) expcnt(7) lgkmcnt(15)
	s_barrier
	s_mov_b64 s[4:5], exec
	v_readlane_b32 s2, v251, 3
	v_readlane_b32 s3, v251, 4
	s_and_b64 s[2:3], s[4:5], s[2:3]
	s_mov_b64 exec, s[2:3]
	s_cbranch_execz .Lxb_done_9
	v_mov_b32_e32 v0, 0
	s_waitcnt vmcnt(0) expcnt(0) lgkmcnt(0)
	ds_read_b32 v2, v0
	ds_read_b32 v1, v0 offset:4
	v_readlane_b32 s0, v251, 2
	v_readlane_b32 s6, v251, 5
	v_readlane_b32 s7, v251, 6
	s_lshl_b32 s0, s0, 8
	s_add_u32 s8, s6, s0
	s_addc_u32 s9, s7, 0
	v_mov_b32_e32 v3, 1
	v_mov_b32_e32 v4, 0x1000
	s_nop 4
	global_atomic_add v3, v4, v3, s[8:9] offset:1024 sc0
	buffer_inv sc1
	s_sub_u32 s10, 8, s66
	s_add_u32 s11, s10, 1
	s_waitcnt lgkmcnt(0)
	v_readfirstlane_b32 s12, v2
	v_readfirstlane_b32 s13, v1
	s_mul_i32 s14, s12, s11
	s_mul_i32 s15, s13, s11
	s_waitcnt vmcnt(0)
	v_readfirstlane_b32 s16, v3
	s_add_u32 s16, s16, 1
	s_cmp_lg_u32 s16, s14
	s_cbranch_scc1 .Lxb_wait_9
	s_waitcnt vmcnt(0)
	v_mov_b32_e32 v3, 1
	v_mov_b32_e32 v4, 0x7f000
	global_atomic_add v3, v4, v3, s[30:31] offset:1024 sc0
	s_waitcnt vmcnt(0)
	v_mov_b32_e32 v3, 1
	v_mov_b32_e32 v4, s0
	v_add_u32_e32 v4, 0x2400, v4
	global_atomic_add v4, v3, s[6:7]

.LBB0_1992:
	s_cmp_gt_i32 s66, 9
	s_cselect_b64 s[0:1], -1, 0
	s_cmp_lt_i32 s67, 10
	s_cselect_b64 s[2:3], -1, 0
	s_or_b64 s[0:1], s[0:1], s[2:3]
	s_and_b64 vcc, exec, s[0:1]
	s_cbranch_vccnz .LBB0_2057
	s_cmpk_gt_i32 s78, 0x1ff
	s_cbranch_scc1 .LBB0_2007
	v_readlane_b32 s4, v250, 6
	v_readlane_b32 s10, v250, 12
	v_readlane_b32 s11, v250, 13
	s_add_u32 s0, s10, 0x2c00
	s_addc_u32 s1, s11, 0
	v_readlane_b32 s5, v250, 7
	s_add_u32 s4, s10, 0x5800
	v_readlane_b32 s6, v250, 8
	s_addc_u32 s5, s11, 0
	v_readlane_b32 s7, v250, 9
	s_add_u32 s6, s10, 0x8400
	v_readlane_b32 s8, v250, 10
	s_addc_u32 s7, s11, 0
	v_readlane_b32 s9, v250, 11
	s_add_u32 s8, s10, 0xb000
	s_addc_u32 s9, s11, 0
	s_add_u32 s10, s10, 0xdc00
	v_readlane_b32 s12, v250, 14
	s_addc_u32 s11, s11, 0
	v_readlane_b32 s13, v250, 15
	s_add_u32 s12, s12, 0x2c00
	s_addc_u32 s13, s13, 0
	s_add_u32 s2, s30, 0x5393e00
	s_addc_u32 s3, s31, 0
	s_lshl_b32 s20, s78, 4
	s_lshl_b32 s21, s64, 4
	s_movk_i32 s22, 0xb0
	s_movk_i32 s23, 0xe0
	s_movk_i32 s24, 0xff
	s_mov_b32 s25, 0xab95000
	v_mov_b32_e32 v0, 0
	s_mov_b32 s26, s78
	s_cmpk_eq_i32 s64, 0x200
	s_cbranch_scc0 .Lp4b_nomap_1
	s_and_b32 s26, s78, 7
	s_lshl_b32 s26, s26, 6
	s_lshr_b32 s20, s78, 3
	s_add_i32 s26, s26, s20
	s_lshl_b32 s20, s26, 4
.Lp4b_nomap_1:
	v_readlane_b32 s14, v250, 16
	v_readlane_b32 s15, v250, 17
	v_readlane_b32 s16, v250, 18
	v_readlane_b32 s17, v250, 19
	v_readlane_b32 s18, v250, 20
	v_readlane_b32 s19, v250, 21
	s_branch .LBB0_1996

.LBB0_2007:
	s_cmp_gt_i32 s67, 10
	s_cbranch_scc0 .LBB0_2057
	s_waitcnt vmcnt(0)
	s_waitcnt vmcnt(63) expcnt(7) lgkmcnt(15)
	s_barrier
	s_mov_b64 s[4:5], exec
	v_readlane_b32 s2, v251, 3
	v_readlane_b32 s3, v251, 4
	s_and_b64 s[2:3], s[4:5], s[2:3]
	s_mov_b64 exec, s[2:3]
	s_cbranch_execz .Lxb_done_10
	v_mov_b32_e32 v0, 0
	s_waitcnt vmcnt(0) expcnt(0) lgkmcnt(0)
	ds_read_b32 v2, v0
	ds_read_b32 v1, v0 offset:4
	v_readlane_b32 s0, v251, 2
	v_readlane_b32 s6, v251, 5
	v_readlane_b32 s7, v251, 6
	s_lshl_b32 s0, s0, 8
	s_add_u32 s8, s6, s0
	s_addc_u32 s9, s7, 0
	v_mov_b32_e32 v3, 1
	v_mov_b32_e32 v4, 0x1000
	s_nop 4
	global_atomic_add v3, v4, v3, s[8:9] offset:1024 sc0
	buffer_inv sc1
	s_sub_u32 s10, 9, s66
	s_add_u32 s11, s10, 1
	s_waitcnt lgkmcnt(0)
	v_readfirstlane_b32 s12, v2
	v_readfirstlane_b32 s13, v1
	s_mul_i32 s14, s12, s11
	s_mul_i32 s15, s13, s11
	s_waitcnt vmcnt(0)
	v_readfirstlane_b32 s16, v3
	s_add_u32 s16, s16, 1
	s_cmp_lg_u32 s16, s14
	s_cbranch_scc1 .Lxb_wait_10
	s_waitcnt vmcnt(0)
	v_mov_b32_e32 v3, 1
	v_mov_b32_e32 v4, 0x7f000
	global_atomic_add v3, v4, v3, s[30:31] offset:1024 sc0
	s_waitcnt vmcnt(0)
	v_mov_b32_e32 v3, 1
	v_mov_b32_e32 v4, s0
	v_add_u32_e32 v4, 0x2400, v4
	global_atomic_add v4, v3, s[6:7]

.LBB0_2123:
	s_cmp_gt_i32 s66, 11
	s_cselect_b64 s[0:1], -1, 0
	s_cmp_lt_i32 s67, 12
	s_cselect_b64 s[2:3], -1, 0
	s_or_b64 s[0:1], s[0:1], s[2:3]
	s_and_b64 vcc, exec, s[0:1]
	s_cbranch_vccnz .LBB0_2177
	v_readlane_b32 s12, v250, 6
	s_cmpk_gt_i32 s78, 0x3ff
	v_readlane_b32 s24, v250, 18
	v_readlane_b32 s25, v250, 19
	v_readlane_b32 s26, v250, 20
	v_readlane_b32 s27, v250, 21
	v_readlane_b32 s13, v250, 7
	v_readlane_b32 s14, v250, 8
	v_readlane_b32 s15, v250, 9
	v_readlane_b32 s16, v250, 10
	v_readlane_b32 s17, v250, 11
	v_readlane_b32 s18, v250, 12
	v_readlane_b32 s19, v250, 13
	v_readlane_b32 s20, v250, 14
	v_readlane_b32 s21, v250, 15
	v_readlane_b32 s22, v250, 16
	v_readlane_b32 s23, v250, 17
	s_cbranch_scc1 .LBB0_2127
	s_mov_b32 s100, s78
	s_mov_b32 s101, s64
	s_movk_i32 s99, 0x3ff
	s_cmpk_eq_i32 s64, 0x200
	s_cbranch_scc0 .Lhm_nomap_1
	s_and_b32 s99, s78, 7
	s_lshl_b32 s99, s99, 7
	s_lshr_b32 s100, s78, 3
	s_add_i32 s100, s100, s99
	s_add_i32 s99, s99, 0x7f
	s_movk_i32 s101, 64
.Lhm_nomap_1:
	s_add_u32 s2, s30, 0x4c000
	s_addc_u32 s3, s31, 0
	s_add_u32 s0, s30, 0xc793e00
	s_addc_u32 s1, s31, 0
	s_lshl_b32 s4, s100, 4
	s_lshl_b32 s5, s100, 3
	s_or_b32 s4, s4, 14
	s_lshl_b32 s11, s101, 4
	s_or_b32 s6, s5, 7
	s_lshl_b32 s14, s101, 3
	s_mov_b32 s9, 0
	s_waitcnt vmcnt(11)
	v_mov_b32_e32 v12, 0
	s_mov_b32 s10, 0x3a800000
	s_mov_b32 s15, 0x800000
	s_movk_i32 s16, 0x1000
	s_mov_b32 s17, s100
.LBB0_2126:
	s_add_i32 s5, s6, 0xffffeff9
	s_lshr_b32 s5, s5, 10
	s_mulk_i32 s5, 0x1800
	s_add_i32 s12, s6, -7
	s_add_i32 s5, s5, 0x9000
	v_mov_b32_e32 v0, v234
	s_cmpk_gt_i32 s17, 0x1ff
	s_cselect_b32 s8, s5, 0x7800
	v_lshlrev_b32_e32 v2, 2, v0
	v_ashrrev_i32_e32 v3, 31, v2
	s_lshl_b64 s[18:19], s[8:9], 2
	v_lshlrev_b64 v[0:1], 2, v[2:3]
	s_add_u32 s18, s30, s18
	v_lshl_add_u64 v[4:5], s[24:25], 0, v[0:1]
	s_addc_u32 s19, s31, s19
	s_ashr_i32 s13, s12, 31
	v_lshl_add_u64 v[10:11], s[26:27], 0, v[0:1]
	global_load_dwordx4 v[6:9], v[4:5], off
	global_load_dwordx4 v[14:17], v[10:11], off
	v_lshl_add_u64 v[4:5], s[18:19], 0, v[0:1]
	s_lshl_b64 s[18:19], s[12:13], 12
	s_add_u32 s18, s28, s18
	v_add_co_u32_e32 v10, vcc, s16, v4
	s_addc_u32 s19, s29, s19
	s_add_i32 s20, s4, -14
	v_addc_co_u32_e32 v11, vcc, 0, v5, vcc
	s_ashr_i32 s21, s20, 31
	global_load_dwordx4 v[18:21], v[4:5], off
	global_load_dwordx4 v[22:25], v[10:11], off
	v_lshl_add_u64 v[4:5], s[18:19], 0, v[0:1]
	s_lshl_b64 s[18:19], s[20:21], 2
	s_add_u32 s18, s2, s18
	s_addc_u32 s19, s3, s19
	global_load_dwordx2 v[30:31], v12, s[18:19]
	s_waitcnt lgkmcnt(0)
	global_load_dwordx4 v[26:29], v[4:5], off
	s_add_i32 s18, s6, -6
	v_lshl_add_u64 v[2:3], v[2:3], 1, s[0:1]
	s_lshl_b64 s[12:13], s[12:13], 11
	s_ashr_i32 s19, s18, 31
	s_waitcnt vmcnt(12)
	v_lshl_add_u64 v[32:33], v[2:3], 0, s[12:13]
	s_lshl_b64 s[12:13], s[18:19], 12
	s_add_u32 s12, s28, s12
	s_addc_u32 s13, s29, s13
	s_add_i32 s20, s4, -12
	s_ashr_i32 s21, s20, 31
	s_waitcnt vmcnt(11)
	v_lshl_add_u64 v[34:35], s[12:13], 0, v[0:1]
	s_lshl_b64 s[12:13], s[20:21], 2
	s_add_u32 s12, s2, s12
	s_addc_u32 s13, s3, s13
	s_waitcnt vmcnt(2)
	v_pk_add_f32 v[10:11], v[22:23], 1.0 op_sel_hi:[1,0]
	s_nop 0
	v_pk_mul_f32 v[4:5], v[10:11], v[6:7]
	v_pk_fma_f32 v[6:7], v[14:15], v[10:11], v[18:19]
	v_pk_add_f32 v[22:23], v[24:25], 1.0 op_sel_hi:[1,0]
	s_waitcnt vmcnt(1)
	v_pk_mul_f32 v[14:15], v[30:31], s[10:11] op_sel_hi:[1,0]
	v_pk_fma_f32 v[10:11], v[16:17], v[22:23], v[20:21]
	v_fma_f32 v13, -v14, v14, v15
	v_max_f32_e32 v13, 0, v13
	v_add_f32_e32 v13, 0x3727c5ac, v13
	v_mul_f32_e32 v15, 0x4b800000, v13
	v_cmp_gt_f32_e32 vcc, s15, v13
	v_pk_mul_f32 v[8:9], v[22:23], v[8:9]
	s_nop 0
	v_cndmask_b32_e32 v13, v13, v15, vcc
	v_rsq_f32_e32 v13, v13
	s_nop 0
	v_mul_f32_e32 v15, 0x45800000, v13
	v_cndmask_b32_e32 v16, v13, v15, vcc
	v_mul_f32_e64 v14, v16, -v14
	s_waitcnt vmcnt(0)
	v_pk_fma_f32 v[18:19], v[26:27], v[16:17], v[14:15] op_sel_hi:[1,0,0]
	v_pk_fma_f32 v[14:15], v[28:29], v[16:17], v[14:15] op_sel_hi:[1,0,0]
	v_pk_fma_f32 v[16:17], v[18:19], v[4:5], v[6:7]
	v_pk_fma_f32 v[14:15], v[14:15], v[8:9], v[10:11]
	v_cvt_pk_bf16_f32 v16, v16, v17
	v_cvt_pk_bf16_f32 v17, v14, v15
	global_store_dwordx2 v[32:33], v[16:17], off
	global_load_dwordx2 v[18:19], v12, s[12:13]
	s_nop 0
	global_load_dwordx4 v[14:17], v[34:35], off
	s_lshl_b64 s[12:13], s[18:19], 11
	s_add_i32 s18, s6, -5
	s_ashr_i32 s19, s18, 31
	v_lshl_add_u64 v[20:21], v[2:3], 0, s[12:13]
	s_lshl_b64 s[12:13], s[18:19], 12
	s_add_u32 s12, s28, s12
	s_addc_u32 s13, s29, s13
	s_add_i32 s20, s4, -10
	s_ashr_i32 s21, s20, 31
	v_lshl_add_u64 v[22:23], s[12:13], 0, v[0:1]
	s_lshl_b64 s[12:13], s[20:21], 2
	s_add_u32 s12, s2, s12
	s_addc_u32 s13, s3, s13
	s_waitcnt vmcnt(1)
	v_pk_mul_f32 v[18:19], v[18:19], s[10:11] op_sel_hi:[1,0]
	s_nop 0
	v_fma_f32 v13, -v18, v18, v19
	v_max_f32_e32 v13, 0, v13
	v_add_f32_e32 v13, 0x3727c5ac, v13
	v_mul_f32_e32 v19, 0x4b800000, v13
	v_cmp_gt_f32_e32 vcc, s15, v13
	s_nop 1
	v_cndmask_b32_e32 v13, v13, v19, vcc
	v_rsq_f32_e32 v13, v13
	s_nop 0
	v_mul_f32_e32 v19, 0x45800000, v13
	v_cndmask_b32_e32 v24, v13, v19, vcc
	v_mul_f32_e64 v18, v24, -v18
	s_waitcnt vmcnt(0)
	v_pk_fma_f32 v[14:15], v[14:15], v[24:25], v[18:19] op_sel_hi:[1,0,0]
	v_pk_fma_f32 v[16:17], v[16:17], v[24:25], v[18:19] op_sel_hi:[1,0,0]
	v_pk_fma_f32 v[14:15], v[14:15], v[4:5], v[6:7]
	v_pk_fma_f32 v[16:17], v[16:17], v[8:9], v[10:11]
	v_cvt_pk_bf16_f32 v14, v14, v15
	v_cvt_pk_bf16_f32 v15, v16, v17
	global_store_dwordx2 v[20:21], v[14:15], off
	global_load_dwordx2 v[18:19], v12, s[12:13]
	s_nop 0
	global_load_dwordx4 v[14:17], v[22:23], off
	s_lshl_b64 s[12:13], s[18:19], 11
	s_add_i32 s18, s6, -4
	s_ashr_i32 s19, s18, 31
	v_lshl_add_u64 v[20:21], v[2:3], 0, s[12:13]
	s_lshl_b64 s[12:13], s[18:19], 12
	s_add_u32 s12, s28, s12
	s_addc_u32 s13, s29, s13
	s_add_i32 s20, s4, -8
	s_ashr_i32 s21, s20, 31
	v_lshl_add_u64 v[22:23], s[12:13], 0, v[0:1]
	s_lshl_b64 s[12:13], s[20:21], 2
	s_add_u32 s12, s2, s12
	s_addc_u32 s13, s3, s13
	s_waitcnt vmcnt(1)
	v_pk_mul_f32 v[18:19], v[18:19], s[10:11] op_sel_hi:[1,0]
	s_nop 0
	v_fma_f32 v13, -v18, v18, v19
	v_max_f32_e32 v13, 0, v13
	v_add_f32_e32 v13, 0x3727c5ac, v13
	v_mul_f32_e32 v19, 0x4b800000, v13
	v_cmp_gt_f32_e32 vcc, s15, v13
	s_nop 1
	v_cndmask_b32_e32 v13, v13, v19, vcc
	v_rsq_f32_e32 v13, v13
	s_nop 0
	v_mul_f32_e32 v19, 0x45800000, v13
	v_cndmask_b32_e32 v24, v13, v19, vcc
	v_mul_f32_e64 v18, v24, -v18
	s_waitcnt vmcnt(0)
	v_pk_fma_f32 v[14:15], v[14:15], v[24:25], v[18:19] op_sel_hi:[1,0,0]
	v_pk_fma_f32 v[16:17], v[16:17], v[24:25], v[18:19] op_sel_hi:[1,0,0]
	v_pk_fma_f32 v[14:15], v[14:15], v[4:5], v[6:7]
	v_pk_fma_f32 v[16:17], v[16:17], v[8:9], v[10:11]
	v_cvt_pk_bf16_f32 v14, v14, v15
	v_cvt_pk_bf16_f32 v15, v16, v17
	global_store_dwordx2 v[20:21], v[14:15], off
	global_load_dwordx2 v[18:19], v12, s[12:13]
	s_nop 0
	global_load_dwordx4 v[14:17], v[22:23], off
	s_lshl_b64 s[12:13], s[18:19], 11
	s_add_i32 s18, s6, -3
	s_ashr_i32 s19, s18, 31
	v_lshl_add_u64 v[20:21], v[2:3], 0, s[12:13]
	s_lshl_b64 s[12:13], s[18:19], 12
	s_add_u32 s12, s28, s12
	s_addc_u32 s13, s29, s13
	s_add_i32 s20, s4, -6
	s_ashr_i32 s21, s20, 31
	v_lshl_add_u64 v[22:23], s[12:13], 0, v[0:1]
	s_lshl_b64 s[12:13], s[20:21], 2
	s_add_u32 s12, s2, s12
	s_addc_u32 s13, s3, s13
	s_waitcnt vmcnt(1)
	v_pk_mul_f32 v[18:19], v[18:19], s[10:11] op_sel_hi:[1,0]
	s_nop 0
	v_fma_f32 v13, -v18, v18, v19
	v_max_f32_e32 v13, 0, v13
	v_add_f32_e32 v13, 0x3727c5ac, v13
	v_mul_f32_e32 v19, 0x4b800000, v13
	v_cmp_gt_f32_e32 vcc, s15, v13
	s_nop 1
	v_cndmask_b32_e32 v13, v13, v19, vcc
	v_rsq_f32_e32 v13, v13
	s_nop 0
	v_mul_f32_e32 v19, 0x45800000, v13
	v_cndmask_b32_e32 v24, v13, v19, vcc
	v_mul_f32_e64 v18, v24, -v18
	s_waitcnt vmcnt(0)
	v_pk_fma_f32 v[14:15], v[14:15], v[24:25], v[18:19] op_sel_hi:[1,0,0]
	v_pk_fma_f32 v[16:17], v[16:17], v[24:25], v[18:19] op_sel_hi:[1,0,0]
	v_pk_fma_f32 v[14:15], v[14:15], v[4:5], v[6:7]
	v_pk_fma_f32 v[16:17], v[16:17], v[8:9], v[10:11]
	v_cvt_pk_bf16_f32 v14, v14, v15
	v_cvt_pk_bf16_f32 v15, v16, v17
	global_store_dwordx2 v[20:21], v[14:15], off
	global_load_dwordx2 v[18:19], v12, s[12:13]
	s_nop 0
	global_load_dwordx4 v[14:17], v[22:23], off
	s_lshl_b64 s[12:13], s[18:19], 11
	s_add_i32 s18, s6, -2
	s_ashr_i32 s19, s18, 31
	v_lshl_add_u64 v[20:21], v[2:3], 0, s[12:13]
	s_lshl_b64 s[12:13], s[18:19], 12
	s_add_u32 s12, s28, s12
	s_addc_u32 s13, s29, s13
	s_add_i32 s20, s4, -4
	s_ashr_i32 s21, s20, 31
	s_lshl_b64 s[20:21], s[20:21], 2
	s_add_u32 s20, s2, s20
	s_addc_u32 s21, s3, s21
	s_waitcnt vmcnt(1)
	v_pk_mul_f32 v[18:19], v[18:19], s[10:11] op_sel_hi:[1,0]
	s_nop 0
	v_fma_f32 v13, -v18, v18, v19
	v_max_f32_e32 v13, 0, v13
	v_add_f32_e32 v13, 0x3727c5ac, v13
	v_mul_f32_e32 v19, 0x4b800000, v13
	v_cmp_gt_f32_e32 vcc, s15, v13
	s_nop 1
	v_cndmask_b32_e32 v13, v13, v19, vcc
	v_rsq_f32_e32 v13, v13
	s_nop 0
	v_mul_f32_e32 v19, 0x45800000, v13
	v_cndmask_b32_e32 v22, v13, v19, vcc
	v_mul_f32_e64 v18, v22, -v18
	s_waitcnt vmcnt(0)
	v_pk_fma_f32 v[14:15], v[14:15], v[22:23], v[18:19] op_sel_hi:[1,0,0]
	v_pk_fma_f32 v[16:17], v[16:17], v[22:23], v[18:19] op_sel_hi:[1,0,0]
	v_pk_fma_f32 v[14:15], v[14:15], v[4:5], v[6:7]
	v_pk_fma_f32 v[16:17], v[16:17], v[8:9], v[10:11]
	v_cvt_pk_bf16_f32 v14, v14, v15
	v_cvt_pk_bf16_f32 v15, v16, v17
	global_store_dwordx2 v[20:21], v[14:15], off
	global_load_dwordx2 v[18:19], v12, s[20:21]
	v_lshl_add_u64 v[14:15], s[12:13], 0, v[0:1]
	global_load_dwordx4 v[14:17], v[14:15], off
	s_lshl_b64 s[12:13], s[18:19], 11
	s_add_i32 s18, s6, -1
	s_ashr_i32 s19, s18, 31
	v_lshl_add_u64 v[20:21], v[2:3], 0, s[12:13]
	s_lshl_b64 s[12:13], s[18:19], 12
	s_add_u32 s12, s28, s12
	s_addc_u32 s13, s29, s13
	s_add_i32 s20, s4, -2
	s_ashr_i32 s21, s20, 31
	s_lshl_b64 s[20:21], s[20:21], 2
	s_add_u32 s20, s2, s20
	s_addc_u32 s21, s3, s21
	s_ashr_i32 s5, s4, 31
	s_ashr_i32 s7, s6, 31
	s_waitcnt vmcnt(1)
	v_pk_mul_f32 v[18:19], v[18:19], s[10:11] op_sel_hi:[1,0]
	s_nop 0
	v_fma_f32 v13, -v18, v18, v19
	v_max_f32_e32 v13, 0, v13
	v_add_f32_e32 v13, 0x3727c5ac, v13
	v_mul_f32_e32 v19, 0x4b800000, v13
	v_cmp_gt_f32_e32 vcc, s15, v13
	s_nop 1
	v_cndmask_b32_e32 v13, v13, v19, vcc
	v_rsq_f32_e32 v13, v13
	s_nop 0
	v_mul_f32_e32 v19, 0x45800000, v13
	v_cndmask_b32_e32 v22, v13, v19, vcc
	v_mul_f32_e64 v18, v22, -v18
	s_waitcnt vmcnt(0)
	v_pk_fma_f32 v[14:15], v[14:15], v[22:23], v[18:19] op_sel_hi:[1,0,0]
	v_pk_fma_f32 v[16:17], v[16:17], v[22:23], v[18:19] op_sel_hi:[1,0,0]
	v_pk_fma_f32 v[14:15], v[14:15], v[4:5], v[6:7]
	v_pk_fma_f32 v[16:17], v[16:17], v[8:9], v[10:11]
	v_cvt_pk_bf16_f32 v14, v14, v15
	v_cvt_pk_bf16_f32 v15, v16, v17
	global_store_dwordx2 v[20:21], v[14:15], off
	global_load_dwordx2 v[18:19], v12, s[20:21]
	v_lshl_add_u64 v[14:15], s[12:13], 0, v[0:1]
	global_load_dwordx4 v[14:17], v[14:15], off
	s_lshl_b64 s[12:13], s[18:19], 11
	v_lshl_add_u64 v[20:21], v[2:3], 0, s[12:13]
	s_lshl_b64 s[12:13], s[4:5], 2
	s_add_u32 s12, s2, s12
	s_addc_u32 s13, s3, s13
	s_waitcnt vmcnt(1)
	v_pk_mul_f32 v[18:19], v[18:19], s[10:11] op_sel_hi:[1,0]
	s_nop 0
	v_fma_f32 v13, -v18, v18, v19
	v_max_f32_e32 v13, 0, v13
	v_add_f32_e32 v13, 0x3727c5ac, v13
	v_mul_f32_e32 v19, 0x4b800000, v13
	v_cmp_gt_f32_e32 vcc, s15, v13
	s_nop 1
	v_cndmask_b32_e32 v13, v13, v19, vcc
	v_rsq_f32_e32 v13, v13
	s_nop 0
	v_mul_f32_e32 v19, 0x45800000, v13
	v_cndmask_b32_e32 v22, v13, v19, vcc
	v_mul_f32_e64 v18, v22, -v18
	s_waitcnt vmcnt(0)
	v_pk_fma_f32 v[14:15], v[14:15], v[22:23], v[18:19] op_sel_hi:[1,0,0]
	v_pk_fma_f32 v[16:17], v[16:17], v[22:23], v[18:19] op_sel_hi:[1,0,0]
	v_pk_fma_f32 v[14:15], v[14:15], v[4:5], v[6:7]
	v_pk_fma_f32 v[16:17], v[16:17], v[8:9], v[10:11]
	v_cvt_pk_bf16_f32 v14, v14, v15
	v_cvt_pk_bf16_f32 v15, v16, v17
	global_store_dwordx2 v[20:21], v[14:15], off
	global_load_dwordx2 v[18:19], v12, s[12:13]
	s_lshl_b64 s[12:13], s[6:7], 12
	s_add_u32 s12, s28, s12
	s_addc_u32 s13, s29, s13
	v_lshl_add_u64 v[0:1], s[12:13], 0, v[0:1]
	global_load_dwordx4 v[14:17], v[0:1], off
	s_lshl_b64 s[12:13], s[6:7], 11
	v_lshl_add_u64 v[0:1], v[2:3], 0, s[12:13]
	s_add_i32 s17, s17, s101
	s_add_i32 s4, s4, s11
	s_add_i32 s6, s6, s14
	s_cmp_gt_i32 s17, s99
	s_waitcnt vmcnt(1)
	v_pk_mul_f32 v[2:3], v[18:19], s[10:11] op_sel_hi:[1,0]
	s_nop 0
	v_fma_f32 v3, -v2, v2, v3
	v_max_f32_e32 v3, 0, v3
	v_add_f32_e32 v3, 0x3727c5ac, v3
	v_mul_f32_e32 v13, 0x4b800000, v3
	v_cmp_gt_f32_e32 vcc, s15, v3
	s_nop 1
	v_cndmask_b32_e32 v3, v3, v13, vcc
	v_rsq_f32_e32 v3, v3
	s_nop 0
	v_mul_f32_e32 v13, 0x45800000, v3
	v_cndmask_b32_e32 v18, v3, v13, vcc
	v_mul_f32_e64 v2, v18, -v2
	s_waitcnt vmcnt(0)
	v_pk_fma_f32 v[14:15], v[14:15], v[18:19], v[2:3] op_sel_hi:[1,0,0]
	v_pk_fma_f32 v[2:3], v[16:17], v[18:19], v[2:3] op_sel_hi:[1,0,0]
	v_pk_fma_f32 v[4:5], v[14:15], v[4:5], v[6:7]
	v_pk_fma_f32 v[2:3], v[2:3], v[8:9], v[10:11]
	v_cvt_pk_bf16_f32 v4, v4, v5
	v_cvt_pk_bf16_f32 v5, v2, v3
	global_store_dwordx2 v[0:1], v[4:5], off
	s_cbranch_scc0 .LBB0_2126
.LBB0_2127:
	s_cmp_gt_u32 s67, 12
	s_cbranch_scc0 .LBB0_2177
	s_waitcnt vmcnt(0)
	s_waitcnt vmcnt(63) expcnt(7) lgkmcnt(15)
	s_barrier
	s_mov_b64 s[4:5], exec
	v_readlane_b32 s2, v251, 3
	v_readlane_b32 s3, v251, 4
	s_and_b64 s[2:3], s[4:5], s[2:3]
	s_mov_b64 exec, s[2:3]
	s_cbranch_execz .Lxb_done_12
	v_mov_b32_e32 v0, 0
	s_waitcnt vmcnt(0) expcnt(0) lgkmcnt(0)
	ds_read_b32 v2, v0
	ds_read_b32 v1, v0 offset:4
	v_readlane_b32 s0, v251, 2
	v_readlane_b32 s6, v251, 5
	v_readlane_b32 s7, v251, 6
	s_lshl_b32 s0, s0, 8
	s_add_u32 s8, s6, s0
	s_addc_u32 s9, s7, 0
	v_mov_b32_e32 v3, 1
	v_mov_b32_e32 v4, 0x1000
	s_nop 4
	global_atomic_add v3, v4, v3, s[8:9] offset:1024 sc0
	buffer_inv sc1
	s_sub_u32 s10, 11, s66
	s_add_u32 s11, s10, 1
	s_waitcnt lgkmcnt(0)
	v_readfirstlane_b32 s12, v2
	v_readfirstlane_b32 s13, v1
	s_mul_i32 s14, s12, s11
	s_mul_i32 s15, s13, s11
	s_waitcnt vmcnt(0)
	v_readfirstlane_b32 s16, v3
	s_add_u32 s16, s16, 1
	s_cmp_lg_u32 s16, s14
	s_cbranch_scc1 .Lxb_wait_12
	s_waitcnt vmcnt(0)
	v_mov_b32_e32 v3, 1
	v_mov_b32_e32 v4, 0x7f000
	global_atomic_add v3, v4, v3, s[30:31] offset:1024 sc0
	s_waitcnt vmcnt(0)
	v_mov_b32_e32 v3, 1
	v_mov_b32_e32 v4, s0
	v_add_u32_e32 v4, 0x2400, v4
	global_atomic_add v4, v3, s[6:7]

.LBB0_3751:
	s_cmp_gt_i32 s67, 16
	s_cbranch_scc0 .LBB0_3801
	s_waitcnt vmcnt(0)
	s_waitcnt vmcnt(63) expcnt(7) lgkmcnt(15)
	s_barrier
	s_mov_b64 s[4:5], exec
	v_readlane_b32 s2, v251, 3
	v_readlane_b32 s3, v251, 4
	s_and_b64 s[2:3], s[4:5], s[2:3]
	s_mov_b64 exec, s[2:3]
	s_cbranch_execz .Lxb_done_16
	v_mov_b32_e32 v0, 0
	s_waitcnt vmcnt(0) expcnt(0) lgkmcnt(0)
	ds_read_b32 v2, v0
	ds_read_b32 v1, v0 offset:4
	v_readlane_b32 s0, v251, 2
	v_readlane_b32 s6, v251, 5
	v_readlane_b32 s7, v251, 6
	s_lshl_b32 s0, s0, 8
	s_add_u32 s8, s6, s0
	s_addc_u32 s9, s7, 0
	v_mov_b32_e32 v3, 1
	v_mov_b32_e32 v4, 0x1000
	s_nop 4
	global_atomic_add v3, v4, v3, s[8:9] offset:1024 sc0
	buffer_inv sc1
	s_sub_u32 s10, 15, s66
	s_add_u32 s11, s10, 1
	s_waitcnt lgkmcnt(0)
	v_readfirstlane_b32 s12, v2
	v_readfirstlane_b32 s13, v1
	s_mul_i32 s14, s12, s11
	s_mul_i32 s15, s13, s11
	s_waitcnt vmcnt(0)
	v_readfirstlane_b32 s16, v3
	s_add_u32 s16, s16, 1
	s_cmp_lg_u32 s16, s14
	s_cbranch_scc1 .Lxb_wait_16
	s_waitcnt vmcnt(0)
	v_mov_b32_e32 v3, 1
	v_mov_b32_e32 v4, 0x7f000
	global_atomic_add v3, v4, v3, s[30:31] offset:1024 sc0
	s_waitcnt vmcnt(0)
	v_mov_b32_e32 v3, 1
	v_mov_b32_e32 v4, s0
	v_add_u32_e32 v4, 0x2400, v4
	global_atomic_add v4, v3, s[6:7]

.LBB0_3817:
	s_cmp_gt_i32 s67, 17
	s_cbranch_scc0 .LBB0_3867
	s_waitcnt vmcnt(0)
	s_waitcnt vmcnt(63) expcnt(7) lgkmcnt(15)
	s_barrier
	s_mov_b64 s[4:5], exec
	v_readlane_b32 s2, v251, 3
	v_readlane_b32 s3, v251, 4
	s_and_b64 s[2:3], s[4:5], s[2:3]
	s_mov_b64 exec, s[2:3]
	s_cbranch_execz .Lxb_done_17
	v_mov_b32_e32 v0, 0
	s_waitcnt vmcnt(0) expcnt(0) lgkmcnt(0)
	ds_read_b32 v2, v0
	ds_read_b32 v1, v0 offset:4
	v_readlane_b32 s0, v251, 2
	v_readlane_b32 s6, v251, 5
	v_readlane_b32 s7, v251, 6
	s_lshl_b32 s0, s0, 8
	s_add_u32 s8, s6, s0
	s_addc_u32 s9, s7, 0
	v_mov_b32_e32 v3, 1
	v_mov_b32_e32 v4, 0x1000
	s_nop 4
	global_atomic_add v3, v4, v3, s[8:9] offset:1024 sc0
	buffer_inv sc1
	s_sub_u32 s10, 16, s66
	s_add_u32 s11, s10, 1
	s_waitcnt lgkmcnt(0)
	v_readfirstlane_b32 s12, v2
	v_readfirstlane_b32 s13, v1
	s_mul_i32 s14, s12, s11
	s_mul_i32 s15, s13, s11
	s_waitcnt vmcnt(0)
	v_readfirstlane_b32 s16, v3
	s_add_u32 s16, s16, 1
	s_cmp_lg_u32 s16, s14
	s_cbranch_scc1 .Lxb_wait_17
	s_waitcnt vmcnt(0)
	v_mov_b32_e32 v3, 1
	v_mov_b32_e32 v4, 0x7f000
	global_atomic_add v3, v4, v3, s[30:31] offset:1024 sc0
	s_waitcnt vmcnt(0)
	v_mov_b32_e32 v3, 1
	v_mov_b32_e32 v4, s0
	v_add_u32_e32 v4, 0x2400, v4
	global_atomic_add v4, v3, s[6:7]

.LBB0_3867:
	s_cmp_gt_i32 s66, 17
	s_cselect_b64 s[0:1], -1, 0
	s_cmp_lt_i32 s67, 18
	s_cselect_b64 s[2:3], -1, 0
	s_or_b64 s[0:1], s[0:1], s[2:3]
	s_and_b64 vcc, exec, s[0:1]
	s_cbranch_vccnz .LBB0_3921
	s_cmpk_gt_i32 s78, 0x3ff
	s_cbranch_scc1 .LBB0_3871
	s_mov_b32 s100, s78
	s_mov_b32 s101, s64
	s_movk_i32 s99, 0x3ff
	s_cmpk_eq_i32 s64, 0x200
	s_cbranch_scc0 .Lhm_nomap_0
	s_and_b32 s99, s78, 7
	s_lshl_b32 s99, s99, 7
	s_lshr_b32 s100, s78, 3
	s_add_i32 s100, s100, s99
	s_add_i32 s99, s99, 0x7f
	s_movk_i32 s101, 64
.Lhm_nomap_0:
	v_readlane_b32 s0, v250, 6
	v_readlane_b32 s1, v250, 7
	s_add_u32 s0, s0, 0x1000
	v_readlane_b32 s2, v250, 8
	v_readlane_b32 s4, v250, 10
	s_addc_u32 s1, s1, 0
	v_readlane_b32 s3, v250, 9
	v_readlane_b32 s5, v250, 11
	s_add_u32 s4, s2, 0x1000
	s_addc_u32 s5, s3, 0
	s_add_u32 s2, s30, 0x5c000
	v_readlane_b32 s6, v250, 12
	s_addc_u32 s3, s31, 0
	v_readlane_b32 s7, v250, 13
	s_add_u32 s6, s30, 0xab93e00
	v_readlane_b32 s15, v250, 21
	s_addc_u32 s7, s31, 0
	v_readlane_b32 s8, v250, 14
	v_readlane_b32 s9, v250, 15
	s_add_u32 s15, s30, 0xd793e00
	v_readlane_b32 s10, v250, 16
	v_readlane_b32 s13, v250, 19
	v_readlane_b32 s14, v250, 20
	s_addc_u32 s18, s31, 0
	s_lshl_b32 s8, s100, 4
	s_lshl_b32 s9, s100, 3
	s_or_b32 s8, s8, 14
	s_lshl_b32 s19, s101, 4
	s_or_b32 s10, s9, 7
	s_lshl_b32 s20, s101, 3
	s_mov_b32 s13, 0
	s_waitcnt vmcnt(11)
	v_mov_b32_e32 v12, 0
	s_mov_b32 s14, 0x3a800000
	s_mov_b32 s21, 0x800000
	s_movk_i32 s22, 0x4000
	s_movk_i32 s23, 0x3000
	s_mov_b32 s24, s100
	v_readlane_b32 s11, v250, 17
	v_readlane_b32 s12, v250, 18
.LBB0_3870:
	s_add_i32 s9, s10, 0xffffeff9
	s_lshr_b32 s9, s9, 10
	s_mulk_i32 s9, 0x1800
	s_add_i32 s16, s10, -7
	s_add_i32 s9, s9, 0x9000
	v_mov_b32_e32 v0, v234
	s_cmpk_gt_i32 s24, 0x1ff
	s_cselect_b32 s12, s9, 0x7800
	v_lshlrev_b32_e32 v2, 2, v0
	v_ashrrev_i32_e32 v3, 31, v2
	s_lshl_b64 s[26:27], s[12:13], 2
	v_lshlrev_b64 v[0:1], 2, v[2:3]
	s_add_u32 s26, s30, s26
	v_lshl_add_u64 v[4:5], s[0:1], 0, v[0:1]
	s_addc_u32 s27, s31, s27
	v_lshl_add_u64 v[10:11], s[4:5], 0, v[0:1]
	global_load_dwordx4 v[6:9], v[4:5], off
	global_load_dwordx4 v[14:17], v[10:11], off
	s_ashr_i32 s17, s16, 31
	v_lshl_add_u64 v[4:5], s[26:27], 0, v[0:1]
	s_lshl_b64 s[26:27], s[16:17], 12
	v_add_co_u32_e32 v10, vcc, s22, v4
	s_add_u32 s26, s15, s26
	s_nop 0
	v_addc_co_u32_e32 v11, vcc, 0, v5, vcc
	v_add_co_u32_e32 v4, vcc, s23, v4
	s_addc_u32 s27, s18, s27
	s_add_i32 s34, s8, -14
	v_addc_co_u32_e32 v5, vcc, 0, v5, vcc
	s_ashr_i32 s35, s34, 31
	global_load_dwordx4 v[18:21], v[10:11], off
	global_load_dwordx4 v[22:25], v[4:5], off
	v_lshl_add_u64 v[4:5], s[26:27], 0, v[0:1]
	s_lshl_b64 s[26:27], s[34:35], 2
	s_add_u32 s26, s2, s26
	s_addc_u32 s27, s3, s27
	global_load_dwordx2 v[30:31], v12, s[26:27]
	s_waitcnt lgkmcnt(0)
	global_load_dwordx4 v[26:29], v[4:5], off
	s_add_i32 s26, s10, -6
	v_lshl_add_u64 v[2:3], v[2:3], 1, s[6:7]
	s_lshl_b64 s[16:17], s[16:17], 11
	s_ashr_i32 s27, s26, 31
	s_waitcnt vmcnt(12)
	v_lshl_add_u64 v[32:33], v[2:3], 0, s[16:17]
	s_lshl_b64 s[16:17], s[26:27], 12
	s_add_u32 s16, s15, s16
	s_addc_u32 s17, s18, s17
	s_add_i32 s34, s8, -12
	s_ashr_i32 s35, s34, 31
	s_waitcnt vmcnt(11)
	v_lshl_add_u64 v[34:35], s[16:17], 0, v[0:1]
	s_lshl_b64 s[16:17], s[34:35], 2
	s_add_u32 s16, s2, s16
	s_addc_u32 s17, s3, s17
	s_waitcnt vmcnt(3)
	v_pk_add_f32 v[10:11], v[18:19], 1.0 op_sel_hi:[1,0]
	s_nop 0
	v_pk_mul_f32 v[4:5], v[10:11], v[6:7]
	s_waitcnt vmcnt(2)
	v_pk_fma_f32 v[6:7], v[14:15], v[10:11], v[22:23]
	v_pk_add_f32 v[18:19], v[20:21], 1.0 op_sel_hi:[1,0]
	s_waitcnt vmcnt(1)
	v_pk_mul_f32 v[14:15], v[30:31], s[14:15] op_sel_hi:[1,0]
	s_nop 0
	v_fma_f32 v13, -v14, v14, v15
	v_max_f32_e32 v13, 0, v13
	v_add_f32_e32 v13, 0x3727c5ac, v13
	v_mul_f32_e32 v15, 0x4b800000, v13
	v_cmp_gt_f32_e32 vcc, s21, v13
	v_pk_fma_f32 v[10:11], v[16:17], v[18:19], v[24:25]
	v_pk_mul_f32 v[8:9], v[18:19], v[8:9]
	v_cndmask_b32_e32 v13, v13, v15, vcc
	v_rsq_f32_e32 v13, v13
	s_nop 0
	v_mul_f32_e32 v15, 0x45800000, v13
	v_cndmask_b32_e32 v16, v13, v15, vcc
	v_mul_f32_e64 v14, v16, -v14
	s_waitcnt vmcnt(0)
	v_pk_fma_f32 v[18:19], v[26:27], v[16:17], v[14:15] op_sel_hi:[1,0,0]
	v_pk_fma_f32 v[14:15], v[28:29], v[16:17], v[14:15] op_sel_hi:[1,0,0]
	v_pk_fma_f32 v[16:17], v[18:19], v[4:5], v[6:7]
	v_pk_fma_f32 v[14:15], v[14:15], v[8:9], v[10:11]
	v_cvt_pk_bf16_f32 v16, v16, v17
	v_cvt_pk_bf16_f32 v17, v14, v15
	global_store_dwordx2 v[32:33], v[16:17], off
	global_load_dwordx2 v[18:19], v12, s[16:17]
	s_nop 0
	global_load_dwordx4 v[14:17], v[34:35], off
	s_lshl_b64 s[16:17], s[26:27], 11
	s_add_i32 s26, s10, -5
	s_ashr_i32 s27, s26, 31
	v_lshl_add_u64 v[20:21], v[2:3], 0, s[16:17]
	s_lshl_b64 s[16:17], s[26:27], 12
	s_add_u32 s16, s15, s16
	s_addc_u32 s17, s18, s17
	s_add_i32 s34, s8, -10
	s_ashr_i32 s35, s34, 31
	v_lshl_add_u64 v[22:23], s[16:17], 0, v[0:1]
	s_lshl_b64 s[16:17], s[34:35], 2
	s_add_u32 s16, s2, s16
	s_addc_u32 s17, s3, s17
	s_waitcnt vmcnt(1)
	v_pk_mul_f32 v[18:19], v[18:19], s[14:15] op_sel_hi:[1,0]
	s_nop 0
	v_fma_f32 v13, -v18, v18, v19
	v_max_f32_e32 v13, 0, v13
	v_add_f32_e32 v13, 0x3727c5ac, v13
	v_mul_f32_e32 v19, 0x4b800000, v13
	v_cmp_gt_f32_e32 vcc, s21, v13
	s_nop 1
	v_cndmask_b32_e32 v13, v13, v19, vcc
	v_rsq_f32_e32 v13, v13
	s_nop 0
	v_mul_f32_e32 v19, 0x45800000, v13
	v_cndmask_b32_e32 v24, v13, v19, vcc
	v_mul_f32_e64 v18, v24, -v18
	s_waitcnt vmcnt(0)
	v_pk_fma_f32 v[14:15], v[14:15], v[24:25], v[18:19] op_sel_hi:[1,0,0]
	v_pk_fma_f32 v[16:17], v[16:17], v[24:25], v[18:19] op_sel_hi:[1,0,0]
	v_pk_fma_f32 v[14:15], v[14:15], v[4:5], v[6:7]
	v_pk_fma_f32 v[16:17], v[16:17], v[8:9], v[10:11]
	v_cvt_pk_bf16_f32 v14, v14, v15
	v_cvt_pk_bf16_f32 v15, v16, v17
	global_store_dwordx2 v[20:21], v[14:15], off
	global_load_dwordx2 v[18:19], v12, s[16:17]
	s_nop 0
	global_load_dwordx4 v[14:17], v[22:23], off
	s_lshl_b64 s[16:17], s[26:27], 11
	s_add_i32 s26, s10, -4
	s_ashr_i32 s27, s26, 31
	v_lshl_add_u64 v[20:21], v[2:3], 0, s[16:17]
	s_lshl_b64 s[16:17], s[26:27], 12
	s_add_u32 s16, s15, s16
	s_addc_u32 s17, s18, s17
	s_add_i32 s34, s8, -8
	s_ashr_i32 s35, s34, 31
	v_lshl_add_u64 v[22:23], s[16:17], 0, v[0:1]
	s_lshl_b64 s[16:17], s[34:35], 2
	s_add_u32 s16, s2, s16
	s_addc_u32 s17, s3, s17
	s_waitcnt vmcnt(1)
	v_pk_mul_f32 v[18:19], v[18:19], s[14:15] op_sel_hi:[1,0]
	s_nop 0
	v_fma_f32 v13, -v18, v18, v19
	v_max_f32_e32 v13, 0, v13
	v_add_f32_e32 v13, 0x3727c5ac, v13
	v_mul_f32_e32 v19, 0x4b800000, v13
	v_cmp_gt_f32_e32 vcc, s21, v13
	s_nop 1
	v_cndmask_b32_e32 v13, v13, v19, vcc
	v_rsq_f32_e32 v13, v13
	s_nop 0
	v_mul_f32_e32 v19, 0x45800000, v13
	v_cndmask_b32_e32 v24, v13, v19, vcc
	v_mul_f32_e64 v18, v24, -v18
	s_waitcnt vmcnt(0)
	v_pk_fma_f32 v[14:15], v[14:15], v[24:25], v[18:19] op_sel_hi:[1,0,0]
	v_pk_fma_f32 v[16:17], v[16:17], v[24:25], v[18:19] op_sel_hi:[1,0,0]
	v_pk_fma_f32 v[14:15], v[14:15], v[4:5], v[6:7]
	v_pk_fma_f32 v[16:17], v[16:17], v[8:9], v[10:11]
	v_cvt_pk_bf16_f32 v14, v14, v15
	v_cvt_pk_bf16_f32 v15, v16, v17
	global_store_dwordx2 v[20:21], v[14:15], off
	global_load_dwordx2 v[18:19], v12, s[16:17]
	s_nop 0
	global_load_dwordx4 v[14:17], v[22:23], off
	s_lshl_b64 s[16:17], s[26:27], 11
	s_add_i32 s26, s10, -3
	s_ashr_i32 s27, s26, 31
	v_lshl_add_u64 v[20:21], v[2:3], 0, s[16:17]
	s_lshl_b64 s[16:17], s[26:27], 12
	s_add_u32 s16, s15, s16
	s_addc_u32 s17, s18, s17
	s_add_i32 s34, s8, -6
	s_ashr_i32 s35, s34, 31
	v_lshl_add_u64 v[22:23], s[16:17], 0, v[0:1]
	s_lshl_b64 s[16:17], s[34:35], 2
	s_add_u32 s16, s2, s16
	s_addc_u32 s17, s3, s17
	s_waitcnt vmcnt(1)
	v_pk_mul_f32 v[18:19], v[18:19], s[14:15] op_sel_hi:[1,0]
	s_nop 0
	v_fma_f32 v13, -v18, v18, v19
	v_max_f32_e32 v13, 0, v13
	v_add_f32_e32 v13, 0x3727c5ac, v13
	v_mul_f32_e32 v19, 0x4b800000, v13
	v_cmp_gt_f32_e32 vcc, s21, v13
	s_nop 1
	v_cndmask_b32_e32 v13, v13, v19, vcc
	v_rsq_f32_e32 v13, v13
	s_nop 0
	v_mul_f32_e32 v19, 0x45800000, v13
	v_cndmask_b32_e32 v24, v13, v19, vcc
	v_mul_f32_e64 v18, v24, -v18
	s_waitcnt vmcnt(0)
	v_pk_fma_f32 v[14:15], v[14:15], v[24:25], v[18:19] op_sel_hi:[1,0,0]
	v_pk_fma_f32 v[16:17], v[16:17], v[24:25], v[18:19] op_sel_hi:[1,0,0]
	v_pk_fma_f32 v[14:15], v[14:15], v[4:5], v[6:7]
	v_pk_fma_f32 v[16:17], v[16:17], v[8:9], v[10:11]
	v_cvt_pk_bf16_f32 v14, v14, v15
	v_cvt_pk_bf16_f32 v15, v16, v17
	global_store_dwordx2 v[20:21], v[14:15], off
	global_load_dwordx2 v[18:19], v12, s[16:17]
	s_nop 0
	global_load_dwordx4 v[14:17], v[22:23], off
	s_lshl_b64 s[16:17], s[26:27], 11
	s_add_i32 s26, s10, -2
	s_ashr_i32 s27, s26, 31
	v_lshl_add_u64 v[20:21], v[2:3], 0, s[16:17]
	s_lshl_b64 s[16:17], s[26:27], 12
	s_add_u32 s16, s15, s16
	s_addc_u32 s17, s18, s17
	s_add_i32 s34, s8, -4
	s_ashr_i32 s35, s34, 31
	s_lshl_b64 s[34:35], s[34:35], 2
	s_add_u32 s34, s2, s34
	s_addc_u32 s35, s3, s35
	s_waitcnt vmcnt(1)
	v_pk_mul_f32 v[18:19], v[18:19], s[14:15] op_sel_hi:[1,0]
	s_nop 0
	v_fma_f32 v13, -v18, v18, v19
	v_max_f32_e32 v13, 0, v13
	v_add_f32_e32 v13, 0x3727c5ac, v13
	v_mul_f32_e32 v19, 0x4b800000, v13
	v_cmp_gt_f32_e32 vcc, s21, v13
	s_nop 1
	v_cndmask_b32_e32 v13, v13, v19, vcc
	v_rsq_f32_e32 v13, v13
	s_nop 0
	v_mul_f32_e32 v19, 0x45800000, v13
	v_cndmask_b32_e32 v22, v13, v19, vcc
	v_mul_f32_e64 v18, v22, -v18
	s_waitcnt vmcnt(0)
	v_pk_fma_f32 v[14:15], v[14:15], v[22:23], v[18:19] op_sel_hi:[1,0,0]
	v_pk_fma_f32 v[16:17], v[16:17], v[22:23], v[18:19] op_sel_hi:[1,0,0]
	v_pk_fma_f32 v[14:15], v[14:15], v[4:5], v[6:7]
	v_pk_fma_f32 v[16:17], v[16:17], v[8:9], v[10:11]
	v_cvt_pk_bf16_f32 v14, v14, v15
	v_cvt_pk_bf16_f32 v15, v16, v17
	global_store_dwordx2 v[20:21], v[14:15], off
	global_load_dwordx2 v[18:19], v12, s[34:35]
	v_lshl_add_u64 v[14:15], s[16:17], 0, v[0:1]
	global_load_dwordx4 v[14:17], v[14:15], off
	s_lshl_b64 s[16:17], s[26:27], 11
	s_add_i32 s26, s10, -1
	s_ashr_i32 s27, s26, 31
	v_lshl_add_u64 v[20:21], v[2:3], 0, s[16:17]
	s_lshl_b64 s[16:17], s[26:27], 12
	s_add_u32 s16, s15, s16
	s_addc_u32 s17, s18, s17
	s_add_i32 s34, s8, -2
	s_ashr_i32 s35, s34, 31
	s_lshl_b64 s[34:35], s[34:35], 2
	s_add_u32 s34, s2, s34
	s_addc_u32 s35, s3, s35
	s_ashr_i32 s9, s8, 31
	s_ashr_i32 s11, s10, 31
	s_waitcnt vmcnt(1)
	v_pk_mul_f32 v[18:19], v[18:19], s[14:15] op_sel_hi:[1,0]
	s_nop 0
	v_fma_f32 v13, -v18, v18, v19
	v_max_f32_e32 v13, 0, v13
	v_add_f32_e32 v13, 0x3727c5ac, v13
	v_mul_f32_e32 v19, 0x4b800000, v13
	v_cmp_gt_f32_e32 vcc, s21, v13
	s_nop 1
	v_cndmask_b32_e32 v13, v13, v19, vcc
	v_rsq_f32_e32 v13, v13
	s_nop 0
	v_mul_f32_e32 v19, 0x45800000, v13
	v_cndmask_b32_e32 v22, v13, v19, vcc
	v_mul_f32_e64 v18, v22, -v18
	s_waitcnt vmcnt(0)
	v_pk_fma_f32 v[14:15], v[14:15], v[22:23], v[18:19] op_sel_hi:[1,0,0]
	v_pk_fma_f32 v[16:17], v[16:17], v[22:23], v[18:19] op_sel_hi:[1,0,0]
	v_pk_fma_f32 v[14:15], v[14:15], v[4:5], v[6:7]
	v_pk_fma_f32 v[16:17], v[16:17], v[8:9], v[10:11]
	v_cvt_pk_bf16_f32 v14, v14, v15
	v_cvt_pk_bf16_f32 v15, v16, v17
	global_store_dwordx2 v[20:21], v[14:15], off
	global_load_dwordx2 v[18:19], v12, s[34:35]
	v_lshl_add_u64 v[14:15], s[16:17], 0, v[0:1]
	global_load_dwordx4 v[14:17], v[14:15], off
	s_lshl_b64 s[16:17], s[26:27], 11
	v_lshl_add_u64 v[20:21], v[2:3], 0, s[16:17]
	s_lshl_b64 s[16:17], s[8:9], 2
	s_add_u32 s16, s2, s16
	s_addc_u32 s17, s3, s17
	s_waitcnt vmcnt(1)
	v_pk_mul_f32 v[18:19], v[18:19], s[14:15] op_sel_hi:[1,0]
	s_nop 0
	v_fma_f32 v13, -v18, v18, v19
	v_max_f32_e32 v13, 0, v13
	v_add_f32_e32 v13, 0x3727c5ac, v13
	v_mul_f32_e32 v19, 0x4b800000, v13
	v_cmp_gt_f32_e32 vcc, s21, v13
	s_nop 1
	v_cndmask_b32_e32 v13, v13, v19, vcc
	v_rsq_f32_e32 v13, v13
	s_nop 0
	v_mul_f32_e32 v19, 0x45800000, v13
	v_cndmask_b32_e32 v22, v13, v19, vcc
	v_mul_f32_e64 v18, v22, -v18
	s_waitcnt vmcnt(0)
	v_pk_fma_f32 v[14:15], v[14:15], v[22:23], v[18:19] op_sel_hi:[1,0,0]
	v_pk_fma_f32 v[16:17], v[16:17], v[22:23], v[18:19] op_sel_hi:[1,0,0]
	v_pk_fma_f32 v[14:15], v[14:15], v[4:5], v[6:7]
	v_pk_fma_f32 v[16:17], v[16:17], v[8:9], v[10:11]
	v_cvt_pk_bf16_f32 v14, v14, v15
	v_cvt_pk_bf16_f32 v15, v16, v17
	global_store_dwordx2 v[20:21], v[14:15], off
	global_load_dwordx2 v[18:19], v12, s[16:17]
	s_lshl_b64 s[16:17], s[10:11], 12
	s_add_u32 s16, s15, s16
	s_addc_u32 s17, s18, s17
	v_lshl_add_u64 v[0:1], s[16:17], 0, v[0:1]
	global_load_dwordx4 v[14:17], v[0:1], off
	s_lshl_b64 s[16:17], s[10:11], 11
	v_lshl_add_u64 v[0:1], v[2:3], 0, s[16:17]
	s_add_i32 s24, s24, s101
	s_add_i32 s8, s8, s19
	s_add_i32 s10, s10, s20
	s_cmp_gt_i32 s24, s99
	s_waitcnt vmcnt(1)
	v_pk_mul_f32 v[2:3], v[18:19], s[14:15] op_sel_hi:[1,0]
	s_nop 0
	v_fma_f32 v3, -v2, v2, v3
	v_max_f32_e32 v3, 0, v3
	v_add_f32_e32 v3, 0x3727c5ac, v3
	v_mul_f32_e32 v13, 0x4b800000, v3
	v_cmp_gt_f32_e32 vcc, s21, v3
	s_nop 1
	v_cndmask_b32_e32 v3, v3, v13, vcc
	v_rsq_f32_e32 v3, v3
	s_nop 0
	v_mul_f32_e32 v13, 0x45800000, v3
	v_cndmask_b32_e32 v18, v3, v13, vcc
	v_mul_f32_e64 v2, v18, -v2
	s_waitcnt vmcnt(0)
	v_pk_fma_f32 v[14:15], v[14:15], v[18:19], v[2:3] op_sel_hi:[1,0,0]
	v_pk_fma_f32 v[2:3], v[16:17], v[18:19], v[2:3] op_sel_hi:[1,0,0]
	v_pk_fma_f32 v[4:5], v[14:15], v[4:5], v[6:7]
	v_pk_fma_f32 v[2:3], v[2:3], v[8:9], v[10:11]
	v_cvt_pk_bf16_f32 v4, v4, v5
	v_cvt_pk_bf16_f32 v5, v2, v3
	global_store_dwordx2 v[0:1], v[4:5], off
	s_cbranch_scc0 .LBB0_3870
.LBB0_3871:
	s_cmp_gt_u32 s67, 18
	s_cbranch_scc0 .LBB0_3921
	s_waitcnt vmcnt(0)
	s_waitcnt vmcnt(63) expcnt(7) lgkmcnt(15)
	s_barrier
	s_mov_b64 s[4:5], exec
	v_readlane_b32 s2, v251, 3
	v_readlane_b32 s3, v251, 4
	s_and_b64 s[2:3], s[4:5], s[2:3]
	s_mov_b64 exec, s[2:3]
	s_cbranch_execz .Lxb_done_18
	v_mov_b32_e32 v0, 0
	s_waitcnt vmcnt(0) expcnt(0) lgkmcnt(0)
	ds_read_b32 v2, v0
	ds_read_b32 v1, v0 offset:4
	v_readlane_b32 s0, v251, 2
	v_readlane_b32 s6, v251, 5
	v_readlane_b32 s7, v251, 6
	s_lshl_b32 s0, s0, 8
	s_add_u32 s8, s6, s0
	s_addc_u32 s9, s7, 0
	v_mov_b32_e32 v3, 1
	v_mov_b32_e32 v4, 0x1000
	s_nop 4
	global_atomic_add v3, v4, v3, s[8:9] offset:1024 sc0
	buffer_inv sc1
	s_sub_u32 s10, 17, s66
	s_add_u32 s11, s10, 1
	s_waitcnt lgkmcnt(0)
	v_readfirstlane_b32 s12, v2
	v_readfirstlane_b32 s13, v1
	s_mul_i32 s14, s12, s11
	s_mul_i32 s15, s13, s11
	s_waitcnt vmcnt(0)
	v_readfirstlane_b32 s16, v3
	s_add_u32 s16, s16, 1
	s_cmp_lg_u32 s16, s14
	s_cbranch_scc1 .Lxb_wait_18
	s_waitcnt vmcnt(0)
	v_mov_b32_e32 v3, 1
	v_mov_b32_e32 v4, 0x7f000
	global_atomic_add v3, v4, v3, s[30:31] offset:1024 sc0
	s_waitcnt vmcnt(0)
	v_mov_b32_e32 v3, 1
	v_mov_b32_e32 v4, s0
	v_add_u32_e32 v4, 0x2400, v4
	global_atomic_add v4, v3, s[6:7]

.LBB0_3931:
	s_cmp_gt_i32 s67, 19
	s_cbranch_scc0 .LBB0_3981
	s_waitcnt vmcnt(0)
	s_waitcnt vmcnt(63) expcnt(7) lgkmcnt(15)
	s_barrier
	s_mov_b64 s[4:5], exec
	v_readlane_b32 s2, v251, 3
	v_readlane_b32 s3, v251, 4
	s_and_b64 s[2:3], s[4:5], s[2:3]
	s_mov_b64 exec, s[2:3]
	s_cbranch_execz .Lxb_done_19
	v_mov_b32_e32 v0, 0
	s_waitcnt vmcnt(0) expcnt(0) lgkmcnt(0)
	ds_read_b32 v2, v0
	ds_read_b32 v1, v0 offset:4
	v_readlane_b32 s0, v251, 2
	v_readlane_b32 s6, v251, 5
	v_readlane_b32 s7, v251, 6
	s_lshl_b32 s0, s0, 8
	s_add_u32 s8, s6, s0
	s_addc_u32 s9, s7, 0
	v_mov_b32_e32 v3, 1
	v_mov_b32_e32 v4, 0x1000
	s_nop 4
	global_atomic_add v3, v4, v3, s[8:9] offset:1024 sc0
	buffer_inv sc1
	s_sub_u32 s10, 18, s66
	s_add_u32 s11, s10, 1
	s_waitcnt lgkmcnt(0)
	v_readfirstlane_b32 s12, v2
	v_readfirstlane_b32 s13, v1
	s_mul_i32 s14, s12, s11
	s_mul_i32 s15, s13, s11
	s_waitcnt vmcnt(0)
	v_readfirstlane_b32 s16, v3
	s_add_u32 s16, s16, 1
	s_cmp_lg_u32 s16, s14
	s_cbranch_scc1 .Lxb_wait_19
	s_waitcnt vmcnt(0)
	v_mov_b32_e32 v3, 1
	v_mov_b32_e32 v4, 0x7f000
	global_atomic_add v3, v4, v3, s[30:31] offset:1024 sc0
	s_waitcnt vmcnt(0)
	v_mov_b32_e32 v3, 1
	v_mov_b32_e32 v4, s0
	v_add_u32_e32 v4, 0x2400, v4
	global_atomic_add v4, v3, s[6:7]

.LBB0_3981:
	s_cmp_gt_i32 s66, 19
	s_cselect_b64 s[0:1], -1, 0
	s_cmp_lt_i32 s67, 20
	s_cselect_b64 s[2:3], -1, 0
	s_or_b64 s[0:1], s[0:1], s[2:3]
	s_and_b64 vcc, exec, s[0:1]
	s_cbranch_vccnz .LBB0_4046
	s_cmpk_gt_i32 s78, 0x1ff
	s_cbranch_scc1 .LBB0_3996
	v_readlane_b32 s8, v250, 6
	v_readlane_b32 s14, v250, 12
	v_readlane_b32 s15, v250, 13
	s_add_u32 s0, s14, 0x10800
	s_addc_u32 s1, s15, 0
	s_add_u32 s4, s14, 0x13400
	s_addc_u32 s5, s15, 0
	s_add_u32 s6, s14, 0x16000
	s_addc_u32 s7, s15, 0
	v_readlane_b32 s9, v250, 7
	s_add_u32 s8, s14, 0x18c00
	v_readlane_b32 s10, v250, 8
	s_addc_u32 s9, s15, 0
	v_readlane_b32 s11, v250, 9
	s_add_u32 s10, s14, 0x1b800
	v_readlane_b32 s12, v250, 10
	s_addc_u32 s11, s15, 0
	v_readlane_b32 s13, v250, 11
	s_add_u32 s12, s14, 0x1e400
	v_readlane_b32 s16, v250, 14
	s_addc_u32 s13, s15, 0
	v_readlane_b32 s17, v250, 15
	s_add_u32 s14, s16, 0x5800
	s_addc_u32 s15, s17, 0
	s_add_u32 s16, s16, 0x8400
	s_addc_u32 s17, s17, 0
	s_add_u32 s2, s30, 0x5393e00
	s_addc_u32 s3, s31, 0
	s_lshl_b32 s24, s78, 4
	s_lshl_b32 s25, s64, 4
	s_movk_i32 s26, 0xb0
	s_movk_i32 s27, 0xe0
	s_movk_i32 s33, 0xff
	s_mov_b32 s34, 0xab95000
	v_mov_b32_e32 v0, 0
	s_mov_b32 s35, s78
	s_cmpk_eq_i32 s64, 0x200
	s_cbranch_scc0 .Lp4b_nomap_0
	s_and_b32 s35, s78, 7
	s_lshl_b32 s35, s35, 6
	s_lshr_b32 s24, s78, 3
	s_add_i32 s35, s35, s24
	s_lshl_b32 s24, s35, 4
.Lp4b_nomap_0:
	v_readlane_b32 s18, v250, 16
	v_readlane_b32 s19, v250, 17
	v_readlane_b32 s20, v250, 18
	v_readlane_b32 s21, v250, 19
	v_readlane_b32 s22, v250, 20
	v_readlane_b32 s23, v250, 21
	s_branch .LBB0_3985

.LBB0_3996:
	s_cmp_gt_i32 s67, 20
	s_cbranch_scc0 .LBB0_4046
	s_waitcnt vmcnt(0)
	s_waitcnt vmcnt(63) expcnt(7) lgkmcnt(15)
	s_barrier
	s_mov_b64 s[4:5], exec
	v_readlane_b32 s2, v251, 3
	v_readlane_b32 s3, v251, 4
	s_and_b64 s[2:3], s[4:5], s[2:3]
	s_mov_b64 exec, s[2:3]
	s_cbranch_execz .Lxb_done_20
	v_mov_b32_e32 v0, 0
	s_waitcnt vmcnt(0) expcnt(0) lgkmcnt(0)
	ds_read_b32 v2, v0
	ds_read_b32 v1, v0 offset:4
	v_readlane_b32 s0, v251, 2
	v_readlane_b32 s6, v251, 5
	v_readlane_b32 s7, v251, 6
	s_lshl_b32 s0, s0, 8
	s_add_u32 s8, s6, s0
	s_addc_u32 s9, s7, 0
	v_mov_b32_e32 v3, 1
	v_mov_b32_e32 v4, 0x1000
	s_nop 4
	global_atomic_add v3, v4, v3, s[8:9] offset:1024 sc0
	buffer_inv sc1
	s_sub_u32 s10, 19, s66
	s_add_u32 s11, s10, 1
	s_waitcnt lgkmcnt(0)
	v_readfirstlane_b32 s12, v2
	v_readfirstlane_b32 s13, v1
	s_mul_i32 s14, s12, s11
	s_mul_i32 s15, s13, s11
	s_waitcnt vmcnt(0)
	v_readfirstlane_b32 s16, v3
	s_add_u32 s16, s16, 1
	s_cmp_lg_u32 s16, s14
	s_cbranch_scc1 .Lxb_wait_20
	s_waitcnt vmcnt(0)
	v_mov_b32_e32 v3, 1
	v_mov_b32_e32 v4, 0x7f000
	global_atomic_add v3, v4, v3, s[30:31] offset:1024 sc0
	s_waitcnt vmcnt(0)
	v_mov_b32_e32 v3, 1
	v_mov_b32_e32 v4, s0
	v_add_u32_e32 v4, 0x2400, v4
	global_atomic_add v4, v3, s[6:7]
